# MODE1 residual epilogue of P3/P9/P12 big GEMM: gate/x loads of 6 column blocks hoisted per 16-row group into dead fragment regs, exact vmcnt waits
# baseline (speedup 1.0000x reference)
.LBB0_534:
	s_bitcmp1_b32 s4, 0
	s_cselect_b32 s21, 0x12000, 0
	v_or_b32_e32 v218, s21, v207
	v_add_u32_e32 v214, v218, v0
	v_add_u32_e32 v246, v218, v167
	ds_read_b128 v[184:187], v214
	ds_read_b128 v[218:221], v246 offset:32768
	ds_read_b128 v[198:201], v214 offset:2048
	ds_read_b128 v[210:213], v214 offset:4096
	ds_read_b128 v[214:217], v214 offset:6144
	ds_read_b128 v[222:225], v246 offset:34816
	ds_read_b128 v[226:229], v246 offset:36864
	ds_read_b128 v[230:233], v246 offset:38912
	ds_read_b128 v[234:237], v246 offset:40960
	ds_read_b128 v[238:241], v246 offset:43008
	ds_read_b128 v[242:245], v246 offset:45056
	ds_read_b128 v[246:249], v246 offset:47104
	s_add_i32 s20, s4, 1
	s_bitcmp1_b32 s20, 0
	s_cselect_b32 s23, 0x12000, 0
	v_add_u32_e32 v171, s23, v166
	v_xor_b32_e32 v169, 64, v207
	v_add3_u32 v169, s21, v167, v169
	s_waitcnt lgkmcnt(10)
	v_mfma_f32_16x16x32_bf16 v[158:161], v[218:221], v[184:187], v[158:161]
	s_waitcnt lgkmcnt(9)
	v_mfma_f32_16x16x32_bf16 v[94:97], v[218:221], v[198:201], v[94:97]
	s_waitcnt lgkmcnt(8)
	v_mfma_f32_16x16x32_bf16 v[62:65], v[218:221], v[210:213], v[62:65]
	s_waitcnt lgkmcnt(7)
	v_mfma_f32_16x16x32_bf16 v[30:33], v[218:221], v[214:217], v[30:33]
	ds_read_b128 v[218:221], v169 offset:32768
	s_waitcnt lgkmcnt(7)
	v_mfma_f32_16x16x32_bf16 v[154:157], v[222:225], v[184:187], v[154:157]
	v_mfma_f32_16x16x32_bf16 v[90:93], v[222:225], v[198:201], v[90:93]
	v_mfma_f32_16x16x32_bf16 v[58:61], v[222:225], v[210:213], v[58:61]
	v_mfma_f32_16x16x32_bf16 v[26:29], v[222:225], v[214:217], v[26:29]
	ds_read_b128 v[222:225], v169 offset:34816
	s_waitcnt lgkmcnt(7)
	v_mfma_f32_16x16x32_bf16 v[150:153], v[226:229], v[184:187], v[150:153]
	v_mfma_f32_16x16x32_bf16 v[86:89], v[226:229], v[198:201], v[86:89]
	v_mfma_f32_16x16x32_bf16 v[54:57], v[226:229], v[210:213], v[54:57]
	v_mfma_f32_16x16x32_bf16 v[22:25], v[226:229], v[214:217], v[22:25]
	ds_read_b128 v[226:229], v169 offset:36864
	s_waitcnt lgkmcnt(7)
	v_mfma_f32_16x16x32_bf16 v[146:149], v[230:233], v[184:187], v[146:149]
	v_mfma_f32_16x16x32_bf16 v[82:85], v[230:233], v[198:201], v[82:85]
	v_mfma_f32_16x16x32_bf16 v[50:53], v[230:233], v[210:213], v[50:53]
	v_mfma_f32_16x16x32_bf16 v[18:21], v[230:233], v[214:217], v[18:21]
	ds_read_b128 v[230:233], v169 offset:38912
	s_waitcnt lgkmcnt(7)
	v_mfma_f32_16x16x32_bf16 v[142:145], v[234:237], v[184:187], v[142:145]
	v_mfma_f32_16x16x32_bf16 v[78:81], v[234:237], v[198:201], v[78:81]
	v_mfma_f32_16x16x32_bf16 v[46:49], v[234:237], v[210:213], v[46:49]
	v_mfma_f32_16x16x32_bf16 v[14:17], v[234:237], v[214:217], v[14:17]
	ds_read_b128 v[234:237], v169 offset:40960
	s_waitcnt lgkmcnt(7)
	v_mfma_f32_16x16x32_bf16 v[138:141], v[238:241], v[184:187], v[138:141]
	v_mfma_f32_16x16x32_bf16 v[74:77], v[238:241], v[198:201], v[74:77]
	v_mfma_f32_16x16x32_bf16 v[42:45], v[238:241], v[210:213], v[42:45]
	v_mfma_f32_16x16x32_bf16 v[10:13], v[238:241], v[214:217], v[10:13]
	ds_read_b128 v[238:241], v169 offset:43008
	s_waitcnt lgkmcnt(7)
	v_mfma_f32_16x16x32_bf16 v[134:137], v[242:245], v[184:187], v[134:137]
	v_mfma_f32_16x16x32_bf16 v[70:73], v[242:245], v[198:201], v[70:73]
	v_mfma_f32_16x16x32_bf16 v[38:41], v[242:245], v[210:213], v[38:41]
	v_mfma_f32_16x16x32_bf16 v[6:9], v[242:245], v[214:217], v[6:9]
	ds_read_b128 v[242:245], v169 offset:45056
	s_waitcnt lgkmcnt(7)
	v_mfma_f32_16x16x32_bf16 v[98:101], v[246:249], v[184:187], v[98:101]
	v_mfma_f32_16x16x32_bf16 v[66:69], v[246:249], v[198:201], v[66:69]
	v_xor_b32_e32 v169, 64, v207
	v_add3_u32 v169, s21, v0, v169
	ds_read_b128 v[184:187], v169
	ds_read_b128 v[198:201], v169 offset:2048
	v_mfma_f32_16x16x32_bf16 v[34:37], v[246:249], v[210:213], v[34:37]
	ds_read_b128 v[210:213], v169 offset:4096
	v_mfma_f32_16x16x32_bf16 v[2:5], v[246:249], v[214:217], v[2:5]
	ds_read_b128 v[214:217], v169 offset:6144
	v_xor_b32_e32 v169, 64, v207
	v_add3_u32 v169, s21, v167, v169
	ds_read_b128 v[246:249], v169 offset:47104
	s_waitcnt lgkmcnt(4)
	v_mfma_f32_16x16x32_bf16 v[158:161], v[218:221], v[184:187], v[158:161]
	s_waitcnt lgkmcnt(3)
	v_mfma_f32_16x16x32_bf16 v[94:97], v[218:221], v[198:201], v[94:97]
	s_waitcnt lgkmcnt(2)
	v_mfma_f32_16x16x32_bf16 v[62:65], v[218:221], v[210:213], v[62:65]
	s_waitcnt lgkmcnt(1)
	v_mfma_f32_16x16x32_bf16 v[30:33], v[218:221], v[214:217], v[30:33]
	s_waitcnt vmcnt(7)
	ds_write_b128 v171, v[110:113]
	v_mfma_f32_16x16x32_bf16 v[154:157], v[222:225], v[184:187], v[154:157]
	v_mfma_f32_16x16x32_bf16 v[90:93], v[222:225], v[198:201], v[90:93]
	global_load_dwordx4 v[110:113], v168, vcc offset:256
	v_mfma_f32_16x16x32_bf16 v[58:61], v[222:225], v[210:213], v[58:61]
	v_mfma_f32_16x16x32_bf16 v[26:29], v[222:225], v[214:217], v[26:29]
	s_waitcnt vmcnt(7)
	ds_write_b128 v171, v[102:105] offset:8192
	v_mfma_f32_16x16x32_bf16 v[150:153], v[226:229], v[184:187], v[150:153]
	v_mfma_f32_16x16x32_bf16 v[86:89], v[226:229], v[198:201], v[86:89]
	v_add_u32_e32 v102, 0x58000, v168
	global_load_dwordx4 v[102:105], v102, vcc offset:256
	v_mfma_f32_16x16x32_bf16 v[54:57], v[226:229], v[210:213], v[54:57]
	v_mfma_f32_16x16x32_bf16 v[22:25], v[226:229], v[214:217], v[22:25]
	s_waitcnt vmcnt(7)
	ds_write_b128 v171, v[106:109] offset:16384
	v_mfma_f32_16x16x32_bf16 v[146:149], v[230:233], v[184:187], v[146:149]
	v_mfma_f32_16x16x32_bf16 v[82:85], v[230:233], v[198:201], v[82:85]
	v_add_u32_e32 v106, 0xb0000, v168
	global_load_dwordx4 v[106:109], v106, vcc offset:256
	v_mfma_f32_16x16x32_bf16 v[50:53], v[230:233], v[210:213], v[50:53]
	v_mfma_f32_16x16x32_bf16 v[18:21], v[230:233], v[214:217], v[18:21]
	s_waitcnt vmcnt(7)
	ds_write_b128 v171, v[122:125] offset:24576
	v_mfma_f32_16x16x32_bf16 v[142:145], v[234:237], v[184:187], v[142:145]
	v_mfma_f32_16x16x32_bf16 v[78:81], v[234:237], v[198:201], v[78:81]
	v_add_u32_e32 v122, 0x108000, v168
	global_load_dwordx4 v[122:125], v122, vcc offset:256
	v_mfma_f32_16x16x32_bf16 v[46:49], v[234:237], v[210:213], v[46:49]
	v_mfma_f32_16x16x32_bf16 v[14:17], v[234:237], v[214:217], v[14:17]
	s_waitcnt vmcnt(7)
	ds_write_b128 v171, v[118:121] offset:32768
	v_mfma_f32_16x16x32_bf16 v[138:141], v[238:241], v[184:187], v[138:141]
	v_mfma_f32_16x16x32_bf16 v[74:77], v[238:241], v[198:201], v[74:77]
	global_load_dwordx4 v[118:121], v170, s[100:101] offset:256
	v_mfma_f32_16x16x32_bf16 v[42:45], v[238:241], v[210:213], v[42:45]
	v_mfma_f32_16x16x32_bf16 v[10:13], v[238:241], v[214:217], v[10:13]
	s_waitcnt vmcnt(7)
	ds_write_b128 v171, v[114:117] offset:40960
	v_mfma_f32_16x16x32_bf16 v[134:137], v[242:245], v[184:187], v[134:137]
	v_mfma_f32_16x16x32_bf16 v[70:73], v[242:245], v[198:201], v[70:73]
	v_add_u32_e32 v114, 0x58000, v170
	global_load_dwordx4 v[114:117], v114, s[100:101] offset:256
	v_mfma_f32_16x16x32_bf16 v[38:41], v[242:245], v[210:213], v[38:41]
	v_mfma_f32_16x16x32_bf16 v[6:9], v[242:245], v[214:217], v[6:9]
	s_waitcnt vmcnt(7)
	ds_write_b128 v171, v[130:133] offset:49152
	s_waitcnt lgkmcnt(7)
	v_mfma_f32_16x16x32_bf16 v[98:101], v[246:249], v[184:187], v[98:101]
	v_mfma_f32_16x16x32_bf16 v[66:69], v[246:249], v[198:201], v[66:69]
	v_add_u32_e32 v130, 0xb0000, v170
	global_load_dwordx4 v[130:133], v130, s[100:101] offset:256
	v_mfma_f32_16x16x32_bf16 v[34:37], v[246:249], v[210:213], v[34:37]
	v_mfma_f32_16x16x32_bf16 v[2:5], v[246:249], v[214:217], v[2:5]
	s_waitcnt vmcnt(7)
	ds_write_b128 v171, v[126:129] offset:57344
	v_add_u32_e32 v126, 0x108000, v170
	global_load_dwordx4 v[126:129], v126, s[100:101] offset:256
	v_add_u32_e32 v168, 0x80, v168
	v_add_u32_e32 v170, 0x80, v170
	s_waitcnt lgkmcnt(0)
	s_barrier
	s_cmp_eq_u32 s20, 44
	s_mov_b32 s4, s20
	s_cbranch_scc0 .LBB0_534
	s_waitcnt vmcnt(4)
	v_add_u32_e32 v102, s7, v206
	v_or_b32_e32 v104, v102, v205
	v_cmp_lt_i32_e32 vcc, s97, v104
	s_waitcnt vmcnt(3)
	v_ashrrev_i32_e32 v106, 31, v104
	v_add_u32_e32 v107, 0xffffc000, v104
	v_ashrrev_i32_e32 v105, 11, v102
	v_cndmask_b32_e64 v111, v106, 0, vcc
	v_cndmask_b32_e32 v110, v104, v107, vcc
	v_mov_b32_e32 v106, s45
	v_mov_b32_e32 v107, s47
	v_mov_b32_e32 v108, s44
	v_mov_b32_e32 v109, s46
	v_or_b32_e32 v102, s6, v208
	s_waitcnt vmcnt(2)
	v_cndmask_b32_e64 v114, v105, 8, vcc
	v_cndmask_b32_e32 v113, v106, v107, vcc
	v_cndmask_b32_e32 v112, v108, v109, vcc
	v_lshlrev_b64 v[122:123], 12, v[110:111]
	v_ashrrev_i32_e32 v103, 31, v102
	v_lshl_add_u64 v[110:111], v[112:113], 0, v[122:123]
	v_mul_hi_i32_i24_e32 v113, 0x9000, v114
	v_mul_i32_i24_e32 v112, 0x9000, v114
	v_lshl_add_u64 v[112:113], s[12:13], 0, v[112:113]
	v_lshlrev_b64 v[102:103], 2, v[102:103]
	s_waitcnt vmcnt(0)
	v_lshl_add_u64 v[124:125], v[112:113], 0, v[102:103]
	global_load_dwordx4 v[184:187], v[124:125], off
	v_lshl_add_u64 v[126:127], v[110:111], 0, v[102:103]
	global_load_dwordx4 v[198:201], v[126:127], off
	global_load_dwordx4 v[210:213], v[124:125], off offset:64
	global_load_dwordx4 v[214:217], v[126:127], off offset:64
	global_load_dwordx4 v[218:221], v[124:125], off offset:128
	global_load_dwordx4 v[222:225], v[126:127], off offset:128
	global_load_dwordx4 v[226:229], v[124:125], off offset:192
	global_load_dwordx4 v[230:233], v[126:127], off offset:192
	global_load_dwordx4 v[234:237], v[124:125], off offset:256
	global_load_dwordx4 v[238:241], v[126:127], off offset:256
	global_load_dwordx4 v[242:245], v[124:125], off offset:320
	global_load_dwordx4 v[246:249], v[126:127], off offset:320
	v_mov_b32_e32 v110, s49
	v_mov_b32_e32 v111, s17
	v_mov_b32_e32 v112, s48
	v_mov_b32_e32 v113, s16
	v_cndmask_b32_e32 v129, v110, v111, vcc
	v_cndmask_b32_e32 v128, v112, v113, vcc
	v_lshl_add_u64 v[122:123], v[128:129], 0, v[122:123]
	v_lshl_add_u64 v[122:123], v[122:123], 0, v[102:103]
	s_waitcnt vmcnt(11)
	v_pk_mul_f32 v[184:185], v[184:185], 0.5 op_sel_hi:[1,0]
	v_pk_mul_f32 v[186:187], v[186:187], 0.5 op_sel_hi:[1,0]
	s_waitcnt vmcnt(10)
	v_pk_fma_f32 v[114:115], v[158:159], v[184:185], v[198:199]
	v_pk_fma_f32 v[116:117], v[160:161], v[186:187], v[200:201]
	global_store_dwordx4 v[122:123], v[114:117], off
	s_nop 0
	s_waitcnt vmcnt(10)
	v_pk_mul_f32 v[210:211], v[210:211], 0.5 op_sel_hi:[1,0]
	v_pk_mul_f32 v[212:213], v[212:213], 0.5 op_sel_hi:[1,0]
	s_waitcnt vmcnt(9)
	v_pk_fma_f32 v[114:115], v[154:155], v[210:211], v[214:215]
	v_pk_fma_f32 v[116:117], v[156:157], v[212:213], v[216:217]
	global_store_dwordx4 v[122:123], v[114:117], off offset:64
	s_nop 0
	global_load_dwordx4 v[184:187], v[124:125], off offset:384
	global_load_dwordx4 v[198:201], v[126:127], off offset:384
	global_load_dwordx4 v[210:213], v[124:125], off offset:448
	global_load_dwordx4 v[214:217], v[126:127], off offset:448
	s_waitcnt vmcnt(13)
	v_pk_mul_f32 v[218:219], v[218:219], 0.5 op_sel_hi:[1,0]
	v_pk_mul_f32 v[220:221], v[220:221], 0.5 op_sel_hi:[1,0]
	s_waitcnt vmcnt(12)
	v_pk_fma_f32 v[114:115], v[150:151], v[218:219], v[222:223]
	v_pk_fma_f32 v[116:117], v[152:153], v[220:221], v[224:225]
	global_store_dwordx4 v[122:123], v[114:117], off offset:128
	s_nop 0
	s_waitcnt vmcnt(12)
	v_pk_mul_f32 v[226:227], v[226:227], 0.5 op_sel_hi:[1,0]
	v_pk_mul_f32 v[228:229], v[228:229], 0.5 op_sel_hi:[1,0]
	s_waitcnt vmcnt(11)
	v_pk_fma_f32 v[114:115], v[146:147], v[226:227], v[230:231]
	v_pk_fma_f32 v[116:117], v[148:149], v[228:229], v[232:233]
	global_store_dwordx4 v[122:123], v[114:117], off offset:192
	s_nop 0
	s_waitcnt vmcnt(11)
	v_pk_mul_f32 v[234:235], v[234:235], 0.5 op_sel_hi:[1,0]
	v_pk_mul_f32 v[236:237], v[236:237], 0.5 op_sel_hi:[1,0]
	s_waitcnt vmcnt(10)
	v_pk_fma_f32 v[114:115], v[142:143], v[234:235], v[238:239]
	v_pk_fma_f32 v[116:117], v[144:145], v[236:237], v[240:241]
	global_store_dwordx4 v[122:123], v[114:117], off offset:256
	s_nop 0
	s_waitcnt vmcnt(10)
	v_pk_mul_f32 v[242:243], v[242:243], 0.5 op_sel_hi:[1,0]
	v_pk_mul_f32 v[244:245], v[244:245], 0.5 op_sel_hi:[1,0]
	s_waitcnt vmcnt(9)
	v_pk_fma_f32 v[114:115], v[138:139], v[242:243], v[246:247]
	v_pk_fma_f32 v[116:117], v[140:141], v[244:245], v[248:249]
	global_store_dwordx4 v[122:123], v[114:117], off offset:320
	s_nop 0
	s_waitcnt vmcnt(7)
	v_pk_mul_f32 v[184:185], v[184:185], 0.5 op_sel_hi:[1,0]
	v_pk_mul_f32 v[186:187], v[186:187], 0.5 op_sel_hi:[1,0]
	s_waitcnt vmcnt(6)
	v_pk_fma_f32 v[114:115], v[134:135], v[184:185], v[198:199]
	v_pk_fma_f32 v[116:117], v[136:137], v[186:187], v[200:201]
	global_store_dwordx4 v[122:123], v[114:117], off offset:384
	s_nop 0
	s_waitcnt vmcnt(6)
	v_pk_mul_f32 v[210:211], v[210:211], 0.5 op_sel_hi:[1,0]
	v_pk_mul_f32 v[212:213], v[212:213], 0.5 op_sel_hi:[1,0]
	s_waitcnt vmcnt(5)
	v_pk_fma_f32 v[98:99], v[98:99], v[210:211], v[214:215]
	v_pk_fma_f32 v[100:101], v[100:101], v[212:213], v[216:217]
	global_store_dwordx4 v[122:123], v[98:101], off offset:448
	s_nop 0
	s_nop 1
	v_or_b32_e32 v98, 16, v104
	v_cmp_lt_i32_e32 vcc, s97, v98
	v_add_u32_e32 v100, 0xffffc010, v104
	v_ashrrev_i32_e32 v99, 31, v98
	v_cndmask_b32_e64 v116, v105, 8, vcc
	v_cndmask_b32_e64 v99, v99, 0, vcc
	v_cndmask_b32_e32 v98, v98, v100, vcc
	v_lshlrev_b64 v[118:119], 12, v[98:99]
	v_mul_hi_i32_i24_e32 v99, 0x9000, v116
	v_mul_i32_i24_e32 v98, 0x9000, v116
	v_cndmask_b32_e32 v101, v106, v107, vcc
	v_cndmask_b32_e32 v100, v108, v109, vcc
	v_lshl_add_u64 v[98:99], s[12:13], 0, v[98:99]
	v_lshl_add_u64 v[114:115], v[100:101], 0, v[118:119]
	v_lshl_add_u64 v[120:121], v[98:99], 0, v[102:103]
	global_load_dwordx4 v[184:187], v[120:121], off
	v_lshl_add_u64 v[122:123], v[114:115], 0, v[102:103]
	global_load_dwordx4 v[198:201], v[122:123], off
	global_load_dwordx4 v[210:213], v[120:121], off offset:64
	global_load_dwordx4 v[214:217], v[122:123], off offset:64
	global_load_dwordx4 v[218:221], v[120:121], off offset:128
	global_load_dwordx4 v[222:225], v[122:123], off offset:128
	global_load_dwordx4 v[226:229], v[120:121], off offset:192
	global_load_dwordx4 v[230:233], v[122:123], off offset:192
	global_load_dwordx4 v[234:237], v[120:121], off offset:256
	global_load_dwordx4 v[238:241], v[122:123], off offset:256
	global_load_dwordx4 v[242:245], v[120:121], off offset:320
	global_load_dwordx4 v[246:249], v[122:123], off offset:320
	v_cndmask_b32_e32 v125, v110, v111, vcc
	v_cndmask_b32_e32 v124, v112, v113, vcc
	v_lshl_add_u64 v[118:119], v[124:125], 0, v[118:119]
	v_lshl_add_u64 v[118:119], v[118:119], 0, v[102:103]
	s_waitcnt vmcnt(11)
	v_pk_mul_f32 v[184:185], v[184:185], 0.5 op_sel_hi:[1,0]
	v_pk_mul_f32 v[186:187], v[186:187], 0.5 op_sel_hi:[1,0]
	s_waitcnt vmcnt(10)
	v_pk_fma_f32 v[94:95], v[94:95], v[184:185], v[198:199]
	v_pk_fma_f32 v[96:97], v[96:97], v[186:187], v[200:201]
	global_store_dwordx4 v[118:119], v[94:97], off
	s_nop 0
	s_waitcnt vmcnt(10)
	v_pk_mul_f32 v[210:211], v[210:211], 0.5 op_sel_hi:[1,0]
	v_pk_mul_f32 v[212:213], v[212:213], 0.5 op_sel_hi:[1,0]
	s_waitcnt vmcnt(9)
	v_pk_fma_f32 v[90:91], v[90:91], v[210:211], v[214:215]
	v_pk_fma_f32 v[92:93], v[92:93], v[212:213], v[216:217]
	global_store_dwordx4 v[118:119], v[90:93], off offset:64
	s_nop 0
	global_load_dwordx4 v[184:187], v[120:121], off offset:384
	global_load_dwordx4 v[198:201], v[122:123], off offset:384
	global_load_dwordx4 v[210:213], v[120:121], off offset:448
	global_load_dwordx4 v[214:217], v[122:123], off offset:448
	s_waitcnt vmcnt(13)
	v_pk_mul_f32 v[218:219], v[218:219], 0.5 op_sel_hi:[1,0]
	v_pk_mul_f32 v[220:221], v[220:221], 0.5 op_sel_hi:[1,0]
	s_waitcnt vmcnt(12)
	v_pk_fma_f32 v[86:87], v[86:87], v[218:219], v[222:223]
	v_pk_fma_f32 v[88:89], v[88:89], v[220:221], v[224:225]
	global_store_dwordx4 v[118:119], v[86:89], off offset:128
	s_nop 0
	s_waitcnt vmcnt(12)
	v_pk_mul_f32 v[226:227], v[226:227], 0.5 op_sel_hi:[1,0]
	v_pk_mul_f32 v[228:229], v[228:229], 0.5 op_sel_hi:[1,0]
	s_waitcnt vmcnt(11)
	v_pk_fma_f32 v[82:83], v[82:83], v[226:227], v[230:231]
	v_pk_fma_f32 v[84:85], v[84:85], v[228:229], v[232:233]
	global_store_dwordx4 v[118:119], v[82:85], off offset:192
	s_nop 0
	s_waitcnt vmcnt(11)
	v_pk_mul_f32 v[234:235], v[234:235], 0.5 op_sel_hi:[1,0]
	v_pk_mul_f32 v[236:237], v[236:237], 0.5 op_sel_hi:[1,0]
	s_waitcnt vmcnt(10)
	v_pk_fma_f32 v[78:79], v[78:79], v[234:235], v[238:239]
	v_pk_fma_f32 v[80:81], v[80:81], v[236:237], v[240:241]
	global_store_dwordx4 v[118:119], v[78:81], off offset:256
	s_nop 0
	s_waitcnt vmcnt(10)
	v_pk_mul_f32 v[242:243], v[242:243], 0.5 op_sel_hi:[1,0]
	v_pk_mul_f32 v[244:245], v[244:245], 0.5 op_sel_hi:[1,0]
	s_waitcnt vmcnt(9)
	v_pk_fma_f32 v[74:75], v[74:75], v[242:243], v[246:247]
	v_pk_fma_f32 v[76:77], v[76:77], v[244:245], v[248:249]
	global_store_dwordx4 v[118:119], v[74:77], off offset:320
	s_nop 0
	s_waitcnt vmcnt(7)
	v_pk_mul_f32 v[184:185], v[184:185], 0.5 op_sel_hi:[1,0]
	v_pk_mul_f32 v[186:187], v[186:187], 0.5 op_sel_hi:[1,0]
	s_waitcnt vmcnt(6)
	v_pk_fma_f32 v[70:71], v[70:71], v[184:185], v[198:199]
	v_pk_fma_f32 v[72:73], v[72:73], v[186:187], v[200:201]
	global_store_dwordx4 v[118:119], v[70:73], off offset:384
	s_nop 0
	s_waitcnt vmcnt(6)
	v_pk_mul_f32 v[210:211], v[210:211], 0.5 op_sel_hi:[1,0]
	v_pk_mul_f32 v[212:213], v[212:213], 0.5 op_sel_hi:[1,0]
	s_waitcnt vmcnt(5)
	v_pk_fma_f32 v[66:67], v[66:67], v[210:211], v[214:215]
	v_pk_fma_f32 v[68:69], v[68:69], v[212:213], v[216:217]
	global_store_dwordx4 v[118:119], v[66:69], off offset:448
	s_nop 0
	s_nop 1
	v_or_b32_e32 v66, 32, v104
	v_cmp_lt_i32_e32 vcc, s97, v66
	v_add_u32_e32 v68, 0xffffc020, v104
	v_ashrrev_i32_e32 v67, 31, v66
	v_cndmask_b32_e64 v72, v105, 8, vcc
	v_cndmask_b32_e64 v67, v67, 0, vcc
	v_cndmask_b32_e32 v66, v66, v68, vcc
	v_lshlrev_b64 v[74:75], 12, v[66:67]
	v_mul_hi_i32_i24_e32 v67, 0x9000, v72
	v_mul_i32_i24_e32 v66, 0x9000, v72
	v_cndmask_b32_e32 v69, v106, v107, vcc
	v_cndmask_b32_e32 v68, v108, v109, vcc
	v_lshl_add_u64 v[66:67], s[12:13], 0, v[66:67]
	v_lshl_add_u64 v[70:71], v[68:69], 0, v[74:75]
	v_lshl_add_u64 v[76:77], v[66:67], 0, v[102:103]
	global_load_dwordx4 v[184:187], v[76:77], off
	v_lshl_add_u64 v[78:79], v[70:71], 0, v[102:103]
	global_load_dwordx4 v[198:201], v[78:79], off
	global_load_dwordx4 v[210:213], v[76:77], off offset:64
	global_load_dwordx4 v[214:217], v[78:79], off offset:64
	global_load_dwordx4 v[218:221], v[76:77], off offset:128
	global_load_dwordx4 v[222:225], v[78:79], off offset:128
	global_load_dwordx4 v[226:229], v[76:77], off offset:192
	global_load_dwordx4 v[230:233], v[78:79], off offset:192
	global_load_dwordx4 v[234:237], v[76:77], off offset:256
	global_load_dwordx4 v[238:241], v[78:79], off offset:256
	global_load_dwordx4 v[242:245], v[76:77], off offset:320
	global_load_dwordx4 v[246:249], v[78:79], off offset:320
	v_cndmask_b32_e32 v81, v110, v111, vcc
	v_cndmask_b32_e32 v80, v112, v113, vcc
	v_lshl_add_u64 v[74:75], v[80:81], 0, v[74:75]
	v_lshl_add_u64 v[74:75], v[74:75], 0, v[102:103]
	s_waitcnt vmcnt(11)
	v_pk_mul_f32 v[184:185], v[184:185], 0.5 op_sel_hi:[1,0]
	v_pk_mul_f32 v[186:187], v[186:187], 0.5 op_sel_hi:[1,0]
	s_waitcnt vmcnt(10)
	v_pk_fma_f32 v[62:63], v[62:63], v[184:185], v[198:199]
	v_pk_fma_f32 v[64:65], v[64:65], v[186:187], v[200:201]
	global_store_dwordx4 v[74:75], v[62:65], off
	s_nop 0
	s_waitcnt vmcnt(10)
	v_pk_mul_f32 v[210:211], v[210:211], 0.5 op_sel_hi:[1,0]
	v_pk_mul_f32 v[212:213], v[212:213], 0.5 op_sel_hi:[1,0]
	s_waitcnt vmcnt(9)
	v_pk_fma_f32 v[58:59], v[58:59], v[210:211], v[214:215]
	v_pk_fma_f32 v[60:61], v[60:61], v[212:213], v[216:217]
	global_store_dwordx4 v[74:75], v[58:61], off offset:64
	s_nop 0
	global_load_dwordx4 v[184:187], v[76:77], off offset:384
	global_load_dwordx4 v[198:201], v[78:79], off offset:384
	global_load_dwordx4 v[210:213], v[76:77], off offset:448
	global_load_dwordx4 v[214:217], v[78:79], off offset:448
	s_waitcnt vmcnt(13)
	v_pk_mul_f32 v[218:219], v[218:219], 0.5 op_sel_hi:[1,0]
	v_pk_mul_f32 v[220:221], v[220:221], 0.5 op_sel_hi:[1,0]
	s_waitcnt vmcnt(12)
	v_pk_fma_f32 v[54:55], v[54:55], v[218:219], v[222:223]
	v_pk_fma_f32 v[56:57], v[56:57], v[220:221], v[224:225]
	global_store_dwordx4 v[74:75], v[54:57], off offset:128
	s_nop 0
	s_waitcnt vmcnt(12)
	v_pk_mul_f32 v[226:227], v[226:227], 0.5 op_sel_hi:[1,0]
	v_pk_mul_f32 v[228:229], v[228:229], 0.5 op_sel_hi:[1,0]
	s_waitcnt vmcnt(11)
	v_pk_fma_f32 v[50:51], v[50:51], v[226:227], v[230:231]
	v_pk_fma_f32 v[52:53], v[52:53], v[228:229], v[232:233]
	global_store_dwordx4 v[74:75], v[50:53], off offset:192
	s_nop 0
	s_waitcnt vmcnt(11)
	v_pk_mul_f32 v[234:235], v[234:235], 0.5 op_sel_hi:[1,0]
	v_pk_mul_f32 v[236:237], v[236:237], 0.5 op_sel_hi:[1,0]
	s_waitcnt vmcnt(10)
	v_pk_fma_f32 v[46:47], v[46:47], v[234:235], v[238:239]
	v_pk_fma_f32 v[48:49], v[48:49], v[236:237], v[240:241]
	global_store_dwordx4 v[74:75], v[46:49], off offset:256
	s_nop 0
	s_waitcnt vmcnt(10)
	v_pk_mul_f32 v[242:243], v[242:243], 0.5 op_sel_hi:[1,0]
	v_pk_mul_f32 v[244:245], v[244:245], 0.5 op_sel_hi:[1,0]
	s_waitcnt vmcnt(9)
	v_pk_fma_f32 v[42:43], v[42:43], v[242:243], v[246:247]
	v_pk_fma_f32 v[44:45], v[44:45], v[244:245], v[248:249]
	global_store_dwordx4 v[74:75], v[42:45], off offset:320
	s_nop 0
	s_waitcnt vmcnt(7)
	v_pk_mul_f32 v[184:185], v[184:185], 0.5 op_sel_hi:[1,0]
	v_pk_mul_f32 v[186:187], v[186:187], 0.5 op_sel_hi:[1,0]
	s_waitcnt vmcnt(6)
	v_pk_fma_f32 v[38:39], v[38:39], v[184:185], v[198:199]
	v_pk_fma_f32 v[40:41], v[40:41], v[186:187], v[200:201]
	global_store_dwordx4 v[74:75], v[38:41], off offset:384
	s_nop 0
	s_waitcnt vmcnt(6)
	v_pk_mul_f32 v[210:211], v[210:211], 0.5 op_sel_hi:[1,0]
	v_pk_mul_f32 v[212:213], v[212:213], 0.5 op_sel_hi:[1,0]
	s_waitcnt vmcnt(5)
	v_pk_fma_f32 v[34:35], v[34:35], v[210:211], v[214:215]
	v_pk_fma_f32 v[36:37], v[36:37], v[212:213], v[216:217]
	global_store_dwordx4 v[74:75], v[34:37], off offset:448
	s_nop 0
	s_nop 1
	v_or_b32_e32 v34, 48, v104
	v_cmp_lt_i32_e32 vcc, s97, v34
	v_add_u32_e32 v36, 0xffffc030, v104
	v_ashrrev_i32_e32 v35, 31, v34
	v_cndmask_b32_e64 v35, v35, 0, vcc
	v_cndmask_b32_e32 v34, v34, v36, vcc
	v_cndmask_b32_e64 v40, v105, 8, vcc
	v_cndmask_b32_e32 v37, v106, v107, vcc
	v_cndmask_b32_e32 v36, v108, v109, vcc
	v_lshlrev_b64 v[34:35], 12, v[34:35]
	v_cndmask_b32_e32 v39, v110, v111, vcc
	v_cndmask_b32_e32 v38, v112, v113, vcc
	v_lshl_add_u64 v[36:37], v[36:37], 0, v[34:35]
	v_lshl_add_u64 v[34:35], v[38:39], 0, v[34:35]
	v_mul_hi_i32_i24_e32 v39, 0x9000, v40
	v_mul_i32_i24_e32 v38, 0x9000, v40
	v_lshl_add_u64 v[38:39], s[12:13], 0, v[38:39]
	v_lshl_add_u64 v[42:43], v[38:39], 0, v[102:103]
	v_lshl_add_u64 v[44:45], v[36:37], 0, v[102:103]
	v_lshl_add_u64 v[46:47], v[34:35], 0, v[102:103]
	global_load_dwordx4 v[184:187], v[42:43], off
	global_load_dwordx4 v[198:201], v[44:45], off
	global_load_dwordx4 v[210:213], v[42:43], off offset:64
	global_load_dwordx4 v[214:217], v[44:45], off offset:64
	global_load_dwordx4 v[218:221], v[42:43], off offset:128
	global_load_dwordx4 v[222:225], v[44:45], off offset:128
	global_load_dwordx4 v[226:229], v[42:43], off offset:192
	global_load_dwordx4 v[230:233], v[44:45], off offset:192
	global_load_dwordx4 v[234:237], v[42:43], off offset:256
	global_load_dwordx4 v[238:241], v[44:45], off offset:256
	global_load_dwordx4 v[242:245], v[42:43], off offset:320
	global_load_dwordx4 v[246:249], v[44:45], off offset:320
	s_waitcnt vmcnt(11)
	v_pk_mul_f32 v[184:185], v[184:185], 0.5 op_sel_hi:[1,0]
	s_waitcnt vmcnt(10)
	v_pk_fma_f32 v[30:31], v[30:31], v[184:185], v[198:199]
	v_pk_mul_f32 v[184:185], v[186:187], 0.5 op_sel_hi:[1,0]
	s_nop 0
	v_pk_fma_f32 v[32:33], v[32:33], v[184:185], v[200:201]
	global_store_dwordx4 v[46:47], v[30:33], off
	s_nop 0
	s_waitcnt vmcnt(10)
	v_pk_mul_f32 v[210:211], v[210:211], 0.5 op_sel_hi:[1,0]
	s_waitcnt vmcnt(9)
	v_pk_fma_f32 v[26:27], v[26:27], v[210:211], v[214:215]
	v_pk_mul_f32 v[210:211], v[212:213], 0.5 op_sel_hi:[1,0]
	s_nop 0
	v_pk_fma_f32 v[28:29], v[28:29], v[210:211], v[216:217]
	global_store_dwordx4 v[46:47], v[26:29], off offset:64
	s_nop 0
	global_load_dwordx4 v[184:187], v[42:43], off offset:384
	global_load_dwordx4 v[198:201], v[44:45], off offset:384
	global_load_dwordx4 v[210:213], v[42:43], off offset:448
	global_load_dwordx4 v[214:217], v[44:45], off offset:448
	s_waitcnt vmcnt(13)
	v_pk_mul_f32 v[218:219], v[218:219], 0.5 op_sel_hi:[1,0]
	s_waitcnt vmcnt(12)
	v_pk_fma_f32 v[22:23], v[22:23], v[218:219], v[222:223]
	v_pk_mul_f32 v[218:219], v[220:221], 0.5 op_sel_hi:[1,0]
	s_nop 0
	v_pk_fma_f32 v[24:25], v[24:25], v[218:219], v[224:225]
	global_store_dwordx4 v[46:47], v[22:25], off offset:128
	s_nop 0
	s_waitcnt vmcnt(12)
	v_pk_mul_f32 v[226:227], v[226:227], 0.5 op_sel_hi:[1,0]
	s_waitcnt vmcnt(11)
	v_pk_fma_f32 v[18:19], v[18:19], v[226:227], v[230:231]
	v_pk_mul_f32 v[226:227], v[228:229], 0.5 op_sel_hi:[1,0]
	s_nop 0
	v_pk_fma_f32 v[20:21], v[20:21], v[226:227], v[232:233]
	global_store_dwordx4 v[46:47], v[18:21], off offset:192
	s_nop 0
	s_waitcnt vmcnt(11)
	v_pk_mul_f32 v[234:235], v[234:235], 0.5 op_sel_hi:[1,0]
	s_waitcnt vmcnt(10)
	v_pk_fma_f32 v[14:15], v[14:15], v[234:235], v[238:239]
	v_pk_mul_f32 v[234:235], v[236:237], 0.5 op_sel_hi:[1,0]
	s_nop 0
	v_pk_fma_f32 v[16:17], v[16:17], v[234:235], v[240:241]
	global_store_dwordx4 v[46:47], v[14:17], off offset:256
	s_nop 0
	s_waitcnt vmcnt(10)
	v_pk_mul_f32 v[242:243], v[242:243], 0.5 op_sel_hi:[1,0]
	s_waitcnt vmcnt(9)
	v_pk_fma_f32 v[10:11], v[10:11], v[242:243], v[246:247]
	v_pk_mul_f32 v[242:243], v[244:245], 0.5 op_sel_hi:[1,0]
	s_nop 0
	v_pk_fma_f32 v[12:13], v[12:13], v[242:243], v[248:249]
	global_store_dwordx4 v[46:47], v[10:13], off offset:320
	s_nop 0
	s_waitcnt vmcnt(7)
	v_pk_mul_f32 v[184:185], v[184:185], 0.5 op_sel_hi:[1,0]
	s_waitcnt vmcnt(6)
	v_pk_fma_f32 v[6:7], v[6:7], v[184:185], v[198:199]
	v_pk_mul_f32 v[184:185], v[186:187], 0.5 op_sel_hi:[1,0]
	s_nop 0
	v_pk_fma_f32 v[8:9], v[8:9], v[184:185], v[200:201]
	global_store_dwordx4 v[46:47], v[6:9], off offset:384
	s_nop 0
	s_waitcnt vmcnt(6)
	v_pk_mul_f32 v[210:211], v[210:211], 0.5 op_sel_hi:[1,0]
	s_waitcnt vmcnt(5)
	v_pk_fma_f32 v[2:3], v[2:3], v[210:211], v[214:215]
	v_pk_mul_f32 v[210:211], v[212:213], 0.5 op_sel_hi:[1,0]
	s_nop 0
	v_pk_fma_f32 v[4:5], v[4:5], v[210:211], v[216:217]
	global_store_dwordx4 v[46:47], v[2:5], off offset:448
	s_nop 0
	s_add_i32 s11, s11, s10
	s_cmpk_gt_i32 s11, 0xff
	s_cbranch_scc0 .LBB0_533

.LBB0_1308:
	s_bitcmp1_b32 s4, 0
	s_cselect_b32 s2, 0x12000, 0
	v_or_b32_e32 v218, s2, v207
	v_add_u32_e32 v214, v218, v0
	v_add_u32_e32 v246, v218, v167
	ds_read_b128 v[184:187], v214
	ds_read_b128 v[218:221], v246 offset:32768
	ds_read_b128 v[198:201], v214 offset:2048
	ds_read_b128 v[210:213], v214 offset:4096
	ds_read_b128 v[214:217], v214 offset:6144
	ds_read_b128 v[222:225], v246 offset:34816
	ds_read_b128 v[226:229], v246 offset:36864
	ds_read_b128 v[230:233], v246 offset:38912
	ds_read_b128 v[234:237], v246 offset:40960
	ds_read_b128 v[238:241], v246 offset:43008
	ds_read_b128 v[242:245], v246 offset:45056
	ds_read_b128 v[246:249], v246 offset:47104
	s_add_i32 s10, s4, 1
	s_bitcmp1_b32 s10, 0
	s_cselect_b32 s3, 0x12000, 0
	v_add_u32_e32 v171, s3, v166
	v_xor_b32_e32 v169, 64, v207
	v_add3_u32 v169, s2, v167, v169
	s_waitcnt lgkmcnt(10)
	v_mfma_f32_16x16x32_bf16 v[158:161], v[218:221], v[184:187], v[158:161]
	s_waitcnt lgkmcnt(9)
	v_mfma_f32_16x16x32_bf16 v[98:101], v[218:221], v[198:201], v[98:101]
	s_waitcnt lgkmcnt(8)
	v_mfma_f32_16x16x32_bf16 v[66:69], v[218:221], v[210:213], v[66:69]
	s_waitcnt lgkmcnt(7)
	v_mfma_f32_16x16x32_bf16 v[34:37], v[218:221], v[214:217], v[34:37]
	ds_read_b128 v[218:221], v169 offset:32768
	s_waitcnt lgkmcnt(7)
	v_mfma_f32_16x16x32_bf16 v[154:157], v[222:225], v[184:187], v[154:157]
	v_mfma_f32_16x16x32_bf16 v[90:93], v[222:225], v[198:201], v[90:93]
	v_mfma_f32_16x16x32_bf16 v[58:61], v[222:225], v[210:213], v[58:61]
	v_mfma_f32_16x16x32_bf16 v[26:29], v[222:225], v[214:217], v[26:29]
	ds_read_b128 v[222:225], v169 offset:34816
	s_waitcnt lgkmcnt(7)
	v_mfma_f32_16x16x32_bf16 v[150:153], v[226:229], v[184:187], v[150:153]
	v_mfma_f32_16x16x32_bf16 v[86:89], v[226:229], v[198:201], v[86:89]
	v_mfma_f32_16x16x32_bf16 v[54:57], v[226:229], v[210:213], v[54:57]
	v_mfma_f32_16x16x32_bf16 v[22:25], v[226:229], v[214:217], v[22:25]
	ds_read_b128 v[226:229], v169 offset:36864
	s_waitcnt lgkmcnt(7)
	v_mfma_f32_16x16x32_bf16 v[146:149], v[230:233], v[184:187], v[146:149]
	v_mfma_f32_16x16x32_bf16 v[82:85], v[230:233], v[198:201], v[82:85]
	v_mfma_f32_16x16x32_bf16 v[50:53], v[230:233], v[210:213], v[50:53]
	v_mfma_f32_16x16x32_bf16 v[18:21], v[230:233], v[214:217], v[18:21]
	ds_read_b128 v[230:233], v169 offset:38912
	s_waitcnt lgkmcnt(7)
	v_mfma_f32_16x16x32_bf16 v[142:145], v[234:237], v[184:187], v[142:145]
	v_mfma_f32_16x16x32_bf16 v[78:81], v[234:237], v[198:201], v[78:81]
	v_mfma_f32_16x16x32_bf16 v[46:49], v[234:237], v[210:213], v[46:49]
	v_mfma_f32_16x16x32_bf16 v[14:17], v[234:237], v[214:217], v[14:17]
	ds_read_b128 v[234:237], v169 offset:40960
	s_waitcnt lgkmcnt(7)
	v_mfma_f32_16x16x32_bf16 v[106:109], v[238:241], v[184:187], v[106:109]
	v_mfma_f32_16x16x32_bf16 v[74:77], v[238:241], v[198:201], v[74:77]
	v_mfma_f32_16x16x32_bf16 v[42:45], v[238:241], v[210:213], v[42:45]
	v_mfma_f32_16x16x32_bf16 v[10:13], v[238:241], v[214:217], v[10:13]
	ds_read_b128 v[238:241], v169 offset:43008
	s_waitcnt lgkmcnt(7)
	v_mfma_f32_16x16x32_bf16 v[102:105], v[242:245], v[184:187], v[102:105]
	v_mfma_f32_16x16x32_bf16 v[70:73], v[242:245], v[198:201], v[70:73]
	v_mfma_f32_16x16x32_bf16 v[38:41], v[242:245], v[210:213], v[38:41]
	v_mfma_f32_16x16x32_bf16 v[6:9], v[242:245], v[214:217], v[6:9]
	ds_read_b128 v[242:245], v169 offset:45056
	s_waitcnt lgkmcnt(7)
	v_mfma_f32_16x16x32_bf16 v[94:97], v[246:249], v[184:187], v[94:97]
	v_mfma_f32_16x16x32_bf16 v[62:65], v[246:249], v[198:201], v[62:65]
	v_xor_b32_e32 v169, 64, v207
	v_add3_u32 v169, s2, v0, v169
	ds_read_b128 v[184:187], v169
	ds_read_b128 v[198:201], v169 offset:2048
	v_mfma_f32_16x16x32_bf16 v[30:33], v[246:249], v[210:213], v[30:33]
	ds_read_b128 v[210:213], v169 offset:4096
	v_mfma_f32_16x16x32_bf16 v[2:5], v[246:249], v[214:217], v[2:5]
	ds_read_b128 v[214:217], v169 offset:6144
	v_xor_b32_e32 v169, 64, v207
	v_add3_u32 v169, s2, v167, v169
	ds_read_b128 v[246:249], v169 offset:47104
	s_waitcnt lgkmcnt(4)
	v_mfma_f32_16x16x32_bf16 v[158:161], v[218:221], v[184:187], v[158:161]
	s_waitcnt lgkmcnt(3)
	v_mfma_f32_16x16x32_bf16 v[98:101], v[218:221], v[198:201], v[98:101]
	s_waitcnt lgkmcnt(2)
	v_mfma_f32_16x16x32_bf16 v[66:69], v[218:221], v[210:213], v[66:69]
	s_waitcnt lgkmcnt(1)
	v_mfma_f32_16x16x32_bf16 v[34:37], v[218:221], v[214:217], v[34:37]
	s_waitcnt vmcnt(7)
	ds_write_b128 v171, v[118:121]
	v_mfma_f32_16x16x32_bf16 v[154:157], v[222:225], v[184:187], v[154:157]
	v_mfma_f32_16x16x32_bf16 v[90:93], v[222:225], v[198:201], v[90:93]
	global_load_dwordx4 v[118:121], v168, vcc offset:256
	v_mfma_f32_16x16x32_bf16 v[58:61], v[222:225], v[210:213], v[58:61]
	v_mfma_f32_16x16x32_bf16 v[26:29], v[222:225], v[214:217], v[26:29]
	s_waitcnt vmcnt(7)
	ds_write_b128 v171, v[110:113] offset:8192
	v_mfma_f32_16x16x32_bf16 v[150:153], v[226:229], v[184:187], v[150:153]
	v_mfma_f32_16x16x32_bf16 v[86:89], v[226:229], v[198:201], v[86:89]
	v_add_u32_e32 v110, s34, v168
	global_load_dwordx4 v[110:113], v110, vcc offset:256
	v_mfma_f32_16x16x32_bf16 v[54:57], v[226:229], v[210:213], v[54:57]
	v_mfma_f32_16x16x32_bf16 v[22:25], v[226:229], v[214:217], v[22:25]
	s_waitcnt vmcnt(7)
	ds_write_b128 v171, v[114:117] offset:16384
	v_mfma_f32_16x16x32_bf16 v[146:149], v[230:233], v[184:187], v[146:149]
	v_mfma_f32_16x16x32_bf16 v[82:85], v[230:233], v[198:201], v[82:85]
	v_add_u32_e32 v114, s35, v168
	global_load_dwordx4 v[114:117], v114, vcc offset:256
	v_mfma_f32_16x16x32_bf16 v[50:53], v[230:233], v[210:213], v[50:53]
	v_mfma_f32_16x16x32_bf16 v[18:21], v[230:233], v[214:217], v[18:21]
	s_waitcnt vmcnt(7)
	ds_write_b128 v171, v[130:133] offset:24576
	v_mfma_f32_16x16x32_bf16 v[142:145], v[234:237], v[184:187], v[142:145]
	v_mfma_f32_16x16x32_bf16 v[78:81], v[234:237], v[198:201], v[78:81]
	v_add_u32_e32 v130, s36, v168
	global_load_dwordx4 v[130:133], v130, vcc offset:256
	v_mfma_f32_16x16x32_bf16 v[46:49], v[234:237], v[210:213], v[46:49]
	v_mfma_f32_16x16x32_bf16 v[14:17], v[234:237], v[214:217], v[14:17]
	s_waitcnt vmcnt(7)
	ds_write_b128 v171, v[126:129] offset:32768
	v_mfma_f32_16x16x32_bf16 v[106:109], v[238:241], v[184:187], v[106:109]
	v_mfma_f32_16x16x32_bf16 v[74:77], v[238:241], v[198:201], v[74:77]
	global_load_dwordx4 v[126:129], v170, s[100:101] offset:256
	v_mfma_f32_16x16x32_bf16 v[42:45], v[238:241], v[210:213], v[42:45]
	v_mfma_f32_16x16x32_bf16 v[10:13], v[238:241], v[214:217], v[10:13]
	s_waitcnt vmcnt(7)
	ds_write_b128 v171, v[122:125] offset:40960
	v_mfma_f32_16x16x32_bf16 v[102:105], v[242:245], v[184:187], v[102:105]
	v_mfma_f32_16x16x32_bf16 v[70:73], v[242:245], v[198:201], v[70:73]
	v_add_u32_e32 v122, s34, v170
	global_load_dwordx4 v[122:125], v122, s[100:101] offset:256
	v_mfma_f32_16x16x32_bf16 v[38:41], v[242:245], v[210:213], v[38:41]
	v_mfma_f32_16x16x32_bf16 v[6:9], v[242:245], v[214:217], v[6:9]
	s_waitcnt vmcnt(7)
	ds_write_b128 v171, v[138:141] offset:49152
	s_waitcnt lgkmcnt(7)
	v_mfma_f32_16x16x32_bf16 v[94:97], v[246:249], v[184:187], v[94:97]
	v_mfma_f32_16x16x32_bf16 v[62:65], v[246:249], v[198:201], v[62:65]
	v_add_u32_e32 v138, s35, v170
	global_load_dwordx4 v[138:141], v138, s[100:101] offset:256
	v_mfma_f32_16x16x32_bf16 v[30:33], v[246:249], v[210:213], v[30:33]
	v_mfma_f32_16x16x32_bf16 v[2:5], v[246:249], v[214:217], v[2:5]
	s_waitcnt vmcnt(7)
	ds_write_b128 v171, v[134:137] offset:57344
	v_add_u32_e32 v134, s36, v170
	global_load_dwordx4 v[134:137], v134, s[100:101] offset:256
	v_add_u32_e32 v168, 0x80, v168
	v_add_u32_e32 v170, 0x80, v170
	s_waitcnt lgkmcnt(0)
	s_barrier
	s_cmp_eq_u32 s10, 16
	s_mov_b32 s4, s10
	s_cbranch_scc0 .LBB0_1308
	s_waitcnt vmcnt(4)
	v_add_u32_e32 v110, s7, v206
	s_waitcnt vmcnt(3)
	v_or_b32_e32 v114, v110, v205
	v_cmp_lt_i32_e32 vcc, s97, v114
	v_ashrrev_i32_e32 v112, 31, v114
	v_add_u32_e32 v116, 0xffffc000, v114
	v_ashrrev_i32_e32 v115, 11, v110
	v_cndmask_b32_e64 v113, v112, 0, vcc
	v_cndmask_b32_e32 v112, v114, v116, vcc
	v_mov_b32_e32 v116, s45
	v_mov_b32_e32 v117, s13
	v_mov_b32_e32 v118, s44
	v_mov_b32_e32 v119, s12
	v_or_b32_e32 v110, s6, v208
	s_waitcnt vmcnt(2)
	v_cndmask_b32_e64 v122, v115, 8, vcc
	v_cndmask_b32_e32 v121, v116, v117, vcc
	v_cndmask_b32_e32 v120, v118, v119, vcc
	v_lshlrev_b64 v[112:113], 12, v[112:113]
	v_ashrrev_i32_e32 v111, 31, v110
	v_lshl_add_u64 v[112:113], v[120:121], 0, v[112:113]
	v_mul_hi_i32_i24_e32 v121, 0x9000, v122
	v_mul_i32_i24_e32 v120, 0x9000, v122
	v_lshl_add_u64 v[120:121], s[14:15], 0, v[120:121]
	v_lshlrev_b64 v[110:111], 2, v[110:111]
	s_waitcnt vmcnt(0)
	v_lshl_add_u64 v[128:129], v[120:121], 0, v[110:111]
	v_lshl_add_u64 v[112:113], v[112:113], 0, v[110:111]
	global_load_dwordx4 v[184:187], v[128:129], off
	global_load_dwordx4 v[198:201], v[112:113], off
	global_load_dwordx4 v[210:213], v[128:129], off offset:64
	global_load_dwordx4 v[214:217], v[112:113], off offset:64
	global_load_dwordx4 v[218:221], v[128:129], off offset:128
	global_load_dwordx4 v[222:225], v[112:113], off offset:128
	global_load_dwordx4 v[226:229], v[128:129], off offset:192
	global_load_dwordx4 v[230:233], v[112:113], off offset:192
	global_load_dwordx4 v[234:237], v[128:129], off offset:256
	global_load_dwordx4 v[238:241], v[112:113], off offset:256
	global_load_dwordx4 v[242:245], v[128:129], off offset:320
	global_load_dwordx4 v[246:249], v[112:113], off offset:320
	s_waitcnt vmcnt(10)
	v_pk_fma_f32 v[120:121], v[158:159], v[184:185], v[198:199]
	v_pk_fma_f32 v[122:123], v[160:161], v[186:187], v[200:201]
	global_store_dwordx4 v[112:113], v[120:123], off
	s_nop 0
	s_waitcnt vmcnt(9)
	v_pk_fma_f32 v[120:121], v[154:155], v[210:211], v[214:215]
	v_pk_fma_f32 v[122:123], v[156:157], v[212:213], v[216:217]
	global_store_dwordx4 v[112:113], v[120:123], off offset:64
	s_nop 0
	global_load_dwordx4 v[184:187], v[128:129], off offset:384
	global_load_dwordx4 v[198:201], v[112:113], off offset:384
	global_load_dwordx4 v[210:213], v[128:129], off offset:448
	global_load_dwordx4 v[214:217], v[112:113], off offset:448
	s_waitcnt vmcnt(12)
	v_pk_fma_f32 v[120:121], v[150:151], v[218:219], v[222:223]
	v_pk_fma_f32 v[122:123], v[152:153], v[220:221], v[224:225]
	global_store_dwordx4 v[112:113], v[120:123], off offset:128
	s_nop 0
	s_waitcnt vmcnt(11)
	v_pk_fma_f32 v[120:121], v[146:147], v[226:227], v[230:231]
	v_pk_fma_f32 v[122:123], v[148:149], v[228:229], v[232:233]
	global_store_dwordx4 v[112:113], v[120:123], off offset:192
	s_nop 0
	s_waitcnt vmcnt(10)
	v_pk_fma_f32 v[120:121], v[142:143], v[234:235], v[238:239]
	v_pk_fma_f32 v[122:123], v[144:145], v[236:237], v[240:241]
	global_store_dwordx4 v[112:113], v[120:123], off offset:256
	s_nop 0
	s_waitcnt vmcnt(9)
	v_pk_fma_f32 v[106:107], v[106:107], v[242:243], v[246:247]
	v_pk_fma_f32 v[108:109], v[108:109], v[244:245], v[248:249]
	global_store_dwordx4 v[112:113], v[106:109], off offset:320
	s_nop 0
	s_waitcnt vmcnt(6)
	v_pk_fma_f32 v[102:103], v[102:103], v[184:185], v[198:199]
	v_pk_fma_f32 v[104:105], v[104:105], v[186:187], v[200:201]
	global_store_dwordx4 v[112:113], v[102:105], off offset:384
	s_nop 0
	s_waitcnt vmcnt(5)
	v_pk_fma_f32 v[94:95], v[94:95], v[210:211], v[214:215]
	v_pk_fma_f32 v[96:97], v[96:97], v[212:213], v[216:217]
	global_store_dwordx4 v[112:113], v[94:97], off offset:448
	s_nop 0
	s_nop 1
	v_or_b32_e32 v94, 16, v114
	v_cmp_lt_i32_e32 vcc, s97, v94
	v_add_u32_e32 v96, 0xffffc010, v114
	v_ashrrev_i32_e32 v95, 31, v94
	v_cndmask_b32_e64 v95, v95, 0, vcc
	v_cndmask_b32_e32 v94, v94, v96, vcc
	v_cndmask_b32_e64 v102, v115, 8, vcc
	v_cndmask_b32_e32 v97, v116, v117, vcc
	v_cndmask_b32_e32 v96, v118, v119, vcc
	v_lshlrev_b64 v[94:95], 12, v[94:95]
	v_lshl_add_u64 v[94:95], v[96:97], 0, v[94:95]
	v_mul_hi_i32_i24_e32 v97, 0x9000, v102
	v_mul_i32_i24_e32 v96, 0x9000, v102
	v_lshl_add_u64 v[96:97], s[14:15], 0, v[96:97]
	v_lshl_add_u64 v[112:113], v[96:97], 0, v[110:111]
	v_lshl_add_u64 v[94:95], v[94:95], 0, v[110:111]
	global_load_dwordx4 v[184:187], v[112:113], off
	global_load_dwordx4 v[198:201], v[94:95], off
	global_load_dwordx4 v[210:213], v[112:113], off offset:64
	global_load_dwordx4 v[214:217], v[94:95], off offset:64
	global_load_dwordx4 v[218:221], v[112:113], off offset:128
	global_load_dwordx4 v[222:225], v[94:95], off offset:128
	global_load_dwordx4 v[226:229], v[112:113], off offset:192
	global_load_dwordx4 v[230:233], v[94:95], off offset:192
	global_load_dwordx4 v[234:237], v[112:113], off offset:256
	global_load_dwordx4 v[238:241], v[94:95], off offset:256
	global_load_dwordx4 v[242:245], v[112:113], off offset:320
	global_load_dwordx4 v[246:249], v[94:95], off offset:320
	s_waitcnt vmcnt(10)
	v_pk_fma_f32 v[96:97], v[98:99], v[184:185], v[198:199]
	v_pk_fma_f32 v[98:99], v[100:101], v[186:187], v[200:201]
	global_store_dwordx4 v[94:95], v[96:99], off
	s_nop 0
	s_waitcnt vmcnt(9)
	v_pk_fma_f32 v[90:91], v[90:91], v[210:211], v[214:215]
	v_pk_fma_f32 v[92:93], v[92:93], v[212:213], v[216:217]
	global_store_dwordx4 v[94:95], v[90:93], off offset:64
	s_nop 0
	global_load_dwordx4 v[184:187], v[112:113], off offset:384
	global_load_dwordx4 v[198:201], v[94:95], off offset:384
	global_load_dwordx4 v[210:213], v[112:113], off offset:448
	global_load_dwordx4 v[214:217], v[94:95], off offset:448
	s_waitcnt vmcnt(12)
	v_pk_fma_f32 v[86:87], v[86:87], v[218:219], v[222:223]
	v_pk_fma_f32 v[88:89], v[88:89], v[220:221], v[224:225]
	global_store_dwordx4 v[94:95], v[86:89], off offset:128
	s_nop 0
	s_waitcnt vmcnt(11)
	v_pk_fma_f32 v[82:83], v[82:83], v[226:227], v[230:231]
	v_pk_fma_f32 v[84:85], v[84:85], v[228:229], v[232:233]
	global_store_dwordx4 v[94:95], v[82:85], off offset:192
	s_nop 0
	s_waitcnt vmcnt(10)
	v_pk_fma_f32 v[78:79], v[78:79], v[234:235], v[238:239]
	v_pk_fma_f32 v[80:81], v[80:81], v[236:237], v[240:241]
	global_store_dwordx4 v[94:95], v[78:81], off offset:256
	s_nop 0
	s_waitcnt vmcnt(9)
	v_pk_fma_f32 v[74:75], v[74:75], v[242:243], v[246:247]
	v_pk_fma_f32 v[76:77], v[76:77], v[244:245], v[248:249]
	global_store_dwordx4 v[94:95], v[74:77], off offset:320
	s_nop 0
	s_waitcnt vmcnt(6)
	v_pk_fma_f32 v[70:71], v[70:71], v[184:185], v[198:199]
	v_pk_fma_f32 v[72:73], v[72:73], v[186:187], v[200:201]
	global_store_dwordx4 v[94:95], v[70:73], off offset:384
	s_nop 0
	s_waitcnt vmcnt(5)
	v_pk_fma_f32 v[62:63], v[62:63], v[210:211], v[214:215]
	v_pk_fma_f32 v[64:65], v[64:65], v[212:213], v[216:217]
	global_store_dwordx4 v[94:95], v[62:65], off offset:448
	s_nop 0
	s_nop 1
	v_or_b32_e32 v62, 32, v114
	v_cmp_lt_i32_e32 vcc, s97, v62
	v_add_u32_e32 v64, 0xffffc020, v114
	v_ashrrev_i32_e32 v63, 31, v62
	v_cndmask_b32_e64 v63, v63, 0, vcc
	v_cndmask_b32_e32 v62, v62, v64, vcc
	v_cndmask_b32_e64 v70, v115, 8, vcc
	v_cndmask_b32_e32 v65, v116, v117, vcc
	v_cndmask_b32_e32 v64, v118, v119, vcc
	v_lshlrev_b64 v[62:63], 12, v[62:63]
	v_lshl_add_u64 v[62:63], v[64:65], 0, v[62:63]
	v_mul_hi_i32_i24_e32 v65, 0x9000, v70
	v_mul_i32_i24_e32 v64, 0x9000, v70
	v_lshl_add_u64 v[64:65], s[14:15], 0, v[64:65]
	v_lshl_add_u64 v[78:79], v[64:65], 0, v[110:111]
	v_lshl_add_u64 v[62:63], v[62:63], 0, v[110:111]
	global_load_dwordx4 v[184:187], v[78:79], off
	global_load_dwordx4 v[198:201], v[62:63], off
	global_load_dwordx4 v[210:213], v[78:79], off offset:64
	global_load_dwordx4 v[214:217], v[62:63], off offset:64
	global_load_dwordx4 v[218:221], v[78:79], off offset:128
	global_load_dwordx4 v[222:225], v[62:63], off offset:128
	global_load_dwordx4 v[226:229], v[78:79], off offset:192
	global_load_dwordx4 v[230:233], v[62:63], off offset:192
	global_load_dwordx4 v[234:237], v[78:79], off offset:256
	global_load_dwordx4 v[238:241], v[62:63], off offset:256
	global_load_dwordx4 v[242:245], v[78:79], off offset:320
	global_load_dwordx4 v[246:249], v[62:63], off offset:320
	s_waitcnt vmcnt(10)
	v_pk_fma_f32 v[64:65], v[66:67], v[184:185], v[198:199]
	v_pk_fma_f32 v[66:67], v[68:69], v[186:187], v[200:201]
	global_store_dwordx4 v[62:63], v[64:67], off
	s_nop 0
	s_waitcnt vmcnt(9)
	v_pk_fma_f32 v[58:59], v[58:59], v[210:211], v[214:215]
	v_pk_fma_f32 v[60:61], v[60:61], v[212:213], v[216:217]
	global_store_dwordx4 v[62:63], v[58:61], off offset:64
	s_nop 0
	global_load_dwordx4 v[184:187], v[78:79], off offset:384
	global_load_dwordx4 v[198:201], v[62:63], off offset:384
	global_load_dwordx4 v[210:213], v[78:79], off offset:448
	global_load_dwordx4 v[214:217], v[62:63], off offset:448
	s_waitcnt vmcnt(12)
	v_pk_fma_f32 v[54:55], v[54:55], v[218:219], v[222:223]
	v_pk_fma_f32 v[56:57], v[56:57], v[220:221], v[224:225]
	global_store_dwordx4 v[62:63], v[54:57], off offset:128
	s_nop 0
	s_waitcnt vmcnt(11)
	v_pk_fma_f32 v[50:51], v[50:51], v[226:227], v[230:231]
	v_pk_fma_f32 v[52:53], v[52:53], v[228:229], v[232:233]
	global_store_dwordx4 v[62:63], v[50:53], off offset:192
	s_nop 0
	s_waitcnt vmcnt(10)
	v_pk_fma_f32 v[46:47], v[46:47], v[234:235], v[238:239]
	v_pk_fma_f32 v[48:49], v[48:49], v[236:237], v[240:241]
	global_store_dwordx4 v[62:63], v[46:49], off offset:256
	s_nop 0
	s_waitcnt vmcnt(9)
	v_pk_fma_f32 v[42:43], v[42:43], v[242:243], v[246:247]
	v_pk_fma_f32 v[44:45], v[44:45], v[244:245], v[248:249]
	global_store_dwordx4 v[62:63], v[42:45], off offset:320
	s_nop 0
	s_waitcnt vmcnt(6)
	v_pk_fma_f32 v[38:39], v[38:39], v[184:185], v[198:199]
	v_pk_fma_f32 v[40:41], v[40:41], v[186:187], v[200:201]
	global_store_dwordx4 v[62:63], v[38:41], off offset:384
	s_nop 0
	s_waitcnt vmcnt(5)
	v_pk_fma_f32 v[30:31], v[30:31], v[210:211], v[214:215]
	v_pk_fma_f32 v[32:33], v[32:33], v[212:213], v[216:217]
	global_store_dwordx4 v[62:63], v[30:33], off offset:448
	s_nop 0
	s_nop 1
	v_or_b32_e32 v30, 48, v114
	v_cmp_lt_i32_e32 vcc, s97, v30
	v_add_u32_e32 v32, 0xffffc030, v114
	v_ashrrev_i32_e32 v31, 31, v30
	v_cndmask_b32_e64 v31, v31, 0, vcc
	v_cndmask_b32_e32 v30, v30, v32, vcc
	v_cndmask_b32_e64 v38, v115, 8, vcc
	v_cndmask_b32_e32 v33, v116, v117, vcc
	v_cndmask_b32_e32 v32, v118, v119, vcc
	v_lshlrev_b64 v[30:31], 12, v[30:31]
	v_lshl_add_u64 v[30:31], v[32:33], 0, v[30:31]
	v_mul_hi_i32_i24_e32 v33, 0x9000, v38
	v_mul_i32_i24_e32 v32, 0x9000, v38
	v_lshl_add_u64 v[32:33], s[14:15], 0, v[32:33]
	v_lshl_add_u64 v[46:47], v[32:33], 0, v[110:111]
	v_lshl_add_u64 v[30:31], v[30:31], 0, v[110:111]
	global_load_dwordx4 v[184:187], v[46:47], off
	global_load_dwordx4 v[198:201], v[30:31], off
	global_load_dwordx4 v[210:213], v[46:47], off offset:64
	global_load_dwordx4 v[214:217], v[30:31], off offset:64
	global_load_dwordx4 v[218:221], v[46:47], off offset:128
	global_load_dwordx4 v[222:225], v[30:31], off offset:128
	global_load_dwordx4 v[226:229], v[46:47], off offset:192
	global_load_dwordx4 v[230:233], v[30:31], off offset:192
	global_load_dwordx4 v[234:237], v[46:47], off offset:256
	global_load_dwordx4 v[238:241], v[30:31], off offset:256
	global_load_dwordx4 v[242:245], v[46:47], off offset:320
	global_load_dwordx4 v[246:249], v[30:31], off offset:320
	s_waitcnt vmcnt(10)
	v_pk_fma_f32 v[32:33], v[34:35], v[184:185], v[198:199]
	v_pk_fma_f32 v[34:35], v[36:37], v[186:187], v[200:201]
	global_store_dwordx4 v[30:31], v[32:35], off
	s_nop 0
	s_waitcnt vmcnt(9)
	v_pk_fma_f32 v[26:27], v[26:27], v[210:211], v[214:215]
	v_pk_fma_f32 v[28:29], v[28:29], v[212:213], v[216:217]
	global_store_dwordx4 v[30:31], v[26:29], off offset:64
	s_nop 0
	global_load_dwordx4 v[184:187], v[46:47], off offset:384
	global_load_dwordx4 v[198:201], v[30:31], off offset:384
	global_load_dwordx4 v[210:213], v[46:47], off offset:448
	global_load_dwordx4 v[214:217], v[30:31], off offset:448
	s_waitcnt vmcnt(12)
	v_pk_fma_f32 v[22:23], v[22:23], v[218:219], v[222:223]
	v_pk_fma_f32 v[24:25], v[24:25], v[220:221], v[224:225]
	global_store_dwordx4 v[30:31], v[22:25], off offset:128
	s_nop 0
	s_waitcnt vmcnt(11)
	v_pk_fma_f32 v[18:19], v[18:19], v[226:227], v[230:231]
	v_pk_fma_f32 v[20:21], v[20:21], v[228:229], v[232:233]
	global_store_dwordx4 v[30:31], v[18:21], off offset:192
	s_nop 0
	s_waitcnt vmcnt(10)
	v_pk_fma_f32 v[14:15], v[14:15], v[234:235], v[238:239]
	v_pk_fma_f32 v[16:17], v[16:17], v[236:237], v[240:241]
	global_store_dwordx4 v[30:31], v[14:17], off offset:256
	s_nop 0
	s_waitcnt vmcnt(9)
	v_pk_fma_f32 v[10:11], v[10:11], v[242:243], v[246:247]
	v_pk_fma_f32 v[12:13], v[12:13], v[244:245], v[248:249]
	global_store_dwordx4 v[30:31], v[10:13], off offset:320
	s_nop 0
	s_waitcnt vmcnt(6)
	v_pk_fma_f32 v[6:7], v[6:7], v[184:185], v[198:199]
	v_pk_fma_f32 v[8:9], v[8:9], v[186:187], v[200:201]
	global_store_dwordx4 v[30:31], v[6:9], off offset:384
	s_nop 0
	s_waitcnt vmcnt(5)
	v_pk_fma_f32 v[2:3], v[2:3], v[210:211], v[214:215]
	v_pk_fma_f32 v[4:5], v[4:5], v[212:213], v[216:217]
	global_store_dwordx4 v[30:31], v[2:5], off offset:448
	s_nop 0
	s_add_i32 s19, s19, s18
	s_cmpk_gt_i32 s19, 0xff
	s_cbranch_scc0 .LBB0_1307

.LBB0_1528:
	s_bitcmp1_b32 s4, 0
	s_cselect_b32 s2, 0x12000, 0
	v_or_b32_e32 v218, s2, v207
	v_add_u32_e32 v214, v218, v0
	v_add_u32_e32 v246, v218, v167
	ds_read_b128 v[184:187], v214
	ds_read_b128 v[218:221], v246 offset:32768
	ds_read_b128 v[198:201], v214 offset:2048
	ds_read_b128 v[210:213], v214 offset:4096
	ds_read_b128 v[214:217], v214 offset:6144
	ds_read_b128 v[222:225], v246 offset:34816
	ds_read_b128 v[226:229], v246 offset:36864
	ds_read_b128 v[230:233], v246 offset:38912
	ds_read_b128 v[234:237], v246 offset:40960
	ds_read_b128 v[238:241], v246 offset:43008
	ds_read_b128 v[242:245], v246 offset:45056
	ds_read_b128 v[246:249], v246 offset:47104
	s_add_i32 s10, s4, 1
	s_bitcmp1_b32 s10, 0
	s_cselect_b32 s3, 0x12000, 0
	v_add_u32_e32 v171, s3, v166
	v_xor_b32_e32 v169, 64, v207
	v_add3_u32 v169, s2, v167, v169
	s_waitcnt lgkmcnt(10)
	v_mfma_f32_16x16x32_bf16 v[158:161], v[218:221], v[184:187], v[158:161]
	s_waitcnt lgkmcnt(9)
	v_mfma_f32_16x16x32_bf16 v[94:97], v[218:221], v[198:201], v[94:97]
	s_waitcnt lgkmcnt(8)
	v_mfma_f32_16x16x32_bf16 v[62:65], v[218:221], v[210:213], v[62:65]
	s_waitcnt lgkmcnt(7)
	v_mfma_f32_16x16x32_bf16 v[30:33], v[218:221], v[214:217], v[30:33]
	ds_read_b128 v[218:221], v169 offset:32768
	s_waitcnt lgkmcnt(7)
	v_mfma_f32_16x16x32_bf16 v[154:157], v[222:225], v[184:187], v[154:157]
	v_mfma_f32_16x16x32_bf16 v[90:93], v[222:225], v[198:201], v[90:93]
	v_mfma_f32_16x16x32_bf16 v[58:61], v[222:225], v[210:213], v[58:61]
	v_mfma_f32_16x16x32_bf16 v[26:29], v[222:225], v[214:217], v[26:29]
	ds_read_b128 v[222:225], v169 offset:34816
	s_waitcnt lgkmcnt(7)
	v_mfma_f32_16x16x32_bf16 v[150:153], v[226:229], v[184:187], v[150:153]
	v_mfma_f32_16x16x32_bf16 v[86:89], v[226:229], v[198:201], v[86:89]
	v_mfma_f32_16x16x32_bf16 v[54:57], v[226:229], v[210:213], v[54:57]
	v_mfma_f32_16x16x32_bf16 v[22:25], v[226:229], v[214:217], v[22:25]
	ds_read_b128 v[226:229], v169 offset:36864
	s_waitcnt lgkmcnt(7)
	v_mfma_f32_16x16x32_bf16 v[146:149], v[230:233], v[184:187], v[146:149]
	v_mfma_f32_16x16x32_bf16 v[82:85], v[230:233], v[198:201], v[82:85]
	v_mfma_f32_16x16x32_bf16 v[50:53], v[230:233], v[210:213], v[50:53]
	v_mfma_f32_16x16x32_bf16 v[18:21], v[230:233], v[214:217], v[18:21]
	ds_read_b128 v[230:233], v169 offset:38912
	s_waitcnt lgkmcnt(7)
	v_mfma_f32_16x16x32_bf16 v[134:137], v[234:237], v[184:187], v[134:137]
	v_mfma_f32_16x16x32_bf16 v[78:81], v[234:237], v[198:201], v[78:81]
	v_mfma_f32_16x16x32_bf16 v[46:49], v[234:237], v[210:213], v[46:49]
	v_mfma_f32_16x16x32_bf16 v[14:17], v[234:237], v[214:217], v[14:17]
	ds_read_b128 v[234:237], v169 offset:40960
	s_waitcnt lgkmcnt(7)
	v_mfma_f32_16x16x32_bf16 v[106:109], v[238:241], v[184:187], v[106:109]
	v_mfma_f32_16x16x32_bf16 v[74:77], v[238:241], v[198:201], v[74:77]
	v_mfma_f32_16x16x32_bf16 v[42:45], v[238:241], v[210:213], v[42:45]
	v_mfma_f32_16x16x32_bf16 v[10:13], v[238:241], v[214:217], v[10:13]
	ds_read_b128 v[238:241], v169 offset:43008
	s_waitcnt lgkmcnt(7)
	v_mfma_f32_16x16x32_bf16 v[102:105], v[242:245], v[184:187], v[102:105]
	v_mfma_f32_16x16x32_bf16 v[70:73], v[242:245], v[198:201], v[70:73]
	v_mfma_f32_16x16x32_bf16 v[38:41], v[242:245], v[210:213], v[38:41]
	v_mfma_f32_16x16x32_bf16 v[6:9], v[242:245], v[214:217], v[6:9]
	ds_read_b128 v[242:245], v169 offset:45056
	s_waitcnt lgkmcnt(7)
	v_mfma_f32_16x16x32_bf16 v[98:101], v[246:249], v[184:187], v[98:101]
	v_mfma_f32_16x16x32_bf16 v[66:69], v[246:249], v[198:201], v[66:69]
	v_xor_b32_e32 v169, 64, v207
	v_add3_u32 v169, s2, v0, v169
	ds_read_b128 v[184:187], v169
	ds_read_b128 v[198:201], v169 offset:2048
	v_mfma_f32_16x16x32_bf16 v[34:37], v[246:249], v[210:213], v[34:37]
	ds_read_b128 v[210:213], v169 offset:4096
	v_mfma_f32_16x16x32_bf16 v[2:5], v[246:249], v[214:217], v[2:5]
	ds_read_b128 v[214:217], v169 offset:6144
	v_xor_b32_e32 v169, 64, v207
	v_add3_u32 v169, s2, v167, v169
	ds_read_b128 v[246:249], v169 offset:47104
	s_waitcnt lgkmcnt(4)
	v_mfma_f32_16x16x32_bf16 v[158:161], v[218:221], v[184:187], v[158:161]
	s_waitcnt lgkmcnt(3)
	v_mfma_f32_16x16x32_bf16 v[94:97], v[218:221], v[198:201], v[94:97]
	s_waitcnt lgkmcnt(2)
	v_mfma_f32_16x16x32_bf16 v[62:65], v[218:221], v[210:213], v[62:65]
	s_waitcnt lgkmcnt(1)
	v_mfma_f32_16x16x32_bf16 v[30:33], v[218:221], v[214:217], v[30:33]
	s_waitcnt vmcnt(7)
	ds_write_b128 v171, v[118:121]
	v_mfma_f32_16x16x32_bf16 v[154:157], v[222:225], v[184:187], v[154:157]
	v_mfma_f32_16x16x32_bf16 v[90:93], v[222:225], v[198:201], v[90:93]
	global_load_dwordx4 v[118:121], v168, vcc offset:256
	v_mfma_f32_16x16x32_bf16 v[58:61], v[222:225], v[210:213], v[58:61]
	v_mfma_f32_16x16x32_bf16 v[26:29], v[222:225], v[214:217], v[26:29]
	s_waitcnt vmcnt(7)
	ds_write_b128 v171, v[110:113] offset:8192
	v_mfma_f32_16x16x32_bf16 v[150:153], v[226:229], v[184:187], v[150:153]
	v_mfma_f32_16x16x32_bf16 v[86:89], v[226:229], v[198:201], v[86:89]
	v_add_u32_e32 v110, 0x58000, v168
	global_load_dwordx4 v[110:113], v110, vcc offset:256
	v_mfma_f32_16x16x32_bf16 v[54:57], v[226:229], v[210:213], v[54:57]
	v_mfma_f32_16x16x32_bf16 v[22:25], v[226:229], v[214:217], v[22:25]
	s_waitcnt vmcnt(7)
	ds_write_b128 v171, v[114:117] offset:16384
	v_mfma_f32_16x16x32_bf16 v[146:149], v[230:233], v[184:187], v[146:149]
	v_mfma_f32_16x16x32_bf16 v[82:85], v[230:233], v[198:201], v[82:85]
	v_add_u32_e32 v114, 0xb0000, v168
	global_load_dwordx4 v[114:117], v114, vcc offset:256
	v_mfma_f32_16x16x32_bf16 v[50:53], v[230:233], v[210:213], v[50:53]
	v_mfma_f32_16x16x32_bf16 v[18:21], v[230:233], v[214:217], v[18:21]
	s_waitcnt vmcnt(7)
	ds_write_b128 v171, v[130:133] offset:24576
	v_mfma_f32_16x16x32_bf16 v[134:137], v[234:237], v[184:187], v[134:137]
	v_mfma_f32_16x16x32_bf16 v[78:81], v[234:237], v[198:201], v[78:81]
	v_add_u32_e32 v130, 0x108000, v168
	global_load_dwordx4 v[130:133], v130, vcc offset:256
	v_mfma_f32_16x16x32_bf16 v[46:49], v[234:237], v[210:213], v[46:49]
	v_mfma_f32_16x16x32_bf16 v[14:17], v[234:237], v[214:217], v[14:17]
	s_waitcnt vmcnt(7)
	ds_write_b128 v171, v[126:129] offset:32768
	v_mfma_f32_16x16x32_bf16 v[106:109], v[238:241], v[184:187], v[106:109]
	v_mfma_f32_16x16x32_bf16 v[74:77], v[238:241], v[198:201], v[74:77]
	global_load_dwordx4 v[126:129], v170, s[100:101] offset:256
	v_mfma_f32_16x16x32_bf16 v[42:45], v[238:241], v[210:213], v[42:45]
	v_mfma_f32_16x16x32_bf16 v[10:13], v[238:241], v[214:217], v[10:13]
	s_waitcnt vmcnt(7)
	ds_write_b128 v171, v[122:125] offset:40960
	v_mfma_f32_16x16x32_bf16 v[102:105], v[242:245], v[184:187], v[102:105]
	v_mfma_f32_16x16x32_bf16 v[70:73], v[242:245], v[198:201], v[70:73]
	v_add_u32_e32 v122, 0x58000, v170
	global_load_dwordx4 v[122:125], v122, s[100:101] offset:256
	v_mfma_f32_16x16x32_bf16 v[38:41], v[242:245], v[210:213], v[38:41]
	v_mfma_f32_16x16x32_bf16 v[6:9], v[242:245], v[214:217], v[6:9]
	s_waitcnt vmcnt(7)
	ds_write_b128 v171, v[142:145] offset:49152
	s_waitcnt lgkmcnt(7)
	v_mfma_f32_16x16x32_bf16 v[98:101], v[246:249], v[184:187], v[98:101]
	v_mfma_f32_16x16x32_bf16 v[66:69], v[246:249], v[198:201], v[66:69]
	v_add_u32_e32 v142, 0xb0000, v170
	global_load_dwordx4 v[142:145], v142, s[100:101] offset:256
	v_mfma_f32_16x16x32_bf16 v[34:37], v[246:249], v[210:213], v[34:37]
	v_mfma_f32_16x16x32_bf16 v[2:5], v[246:249], v[214:217], v[2:5]
	s_waitcnt vmcnt(7)
	ds_write_b128 v171, v[138:141] offset:57344
	v_add_u32_e32 v138, 0x108000, v170
	global_load_dwordx4 v[138:141], v138, s[100:101] offset:256
	v_add_u32_e32 v168, 0x80, v168
	v_add_u32_e32 v170, 0x80, v170
	s_waitcnt lgkmcnt(0)
	s_barrier
	s_cmp_eq_u32 s10, 44
	s_mov_b32 s4, s10
	s_cbranch_scc0 .LBB0_1528
	s_waitcnt vmcnt(4)
	v_add_u32_e32 v110, s7, v206
	s_waitcnt vmcnt(3)
	v_or_b32_e32 v114, v110, v205
	v_cmp_lt_i32_e32 vcc, s97, v114
	v_ashrrev_i32_e32 v112, 31, v114
	v_add_u32_e32 v116, 0xffffc000, v114
	v_ashrrev_i32_e32 v115, 11, v110
	v_cndmask_b32_e64 v113, v112, 0, vcc
	v_cndmask_b32_e32 v112, v114, v116, vcc
	v_mov_b32_e32 v116, s45
	v_mov_b32_e32 v117, s13
	v_mov_b32_e32 v118, s44
	v_mov_b32_e32 v119, s12
	v_or_b32_e32 v110, s6, v208
	s_waitcnt vmcnt(2)
	v_cndmask_b32_e64 v122, v115, 8, vcc
	v_cndmask_b32_e32 v121, v116, v117, vcc
	v_cndmask_b32_e32 v120, v118, v119, vcc
	v_lshlrev_b64 v[112:113], 12, v[112:113]
	v_ashrrev_i32_e32 v111, 31, v110
	v_lshl_add_u64 v[112:113], v[120:121], 0, v[112:113]
	v_mul_hi_i32_i24_e32 v121, 0x9000, v122
	v_mul_i32_i24_e32 v120, 0x9000, v122
	v_lshl_add_u64 v[120:121], s[14:15], 0, v[120:121]
	v_lshlrev_b64 v[110:111], 2, v[110:111]
	s_waitcnt vmcnt(0)
	v_lshl_add_u64 v[128:129], v[120:121], 0, v[110:111]
	global_load_dwordx4 v[184:187], v[128:129], off
	v_lshl_add_u64 v[112:113], v[112:113], 0, v[110:111]
	global_load_dwordx4 v[198:201], v[112:113], off
	global_load_dwordx4 v[210:213], v[128:129], off offset:64
	global_load_dwordx4 v[214:217], v[112:113], off offset:64
	global_load_dwordx4 v[218:221], v[128:129], off offset:128
	global_load_dwordx4 v[222:225], v[112:113], off offset:128
	global_load_dwordx4 v[226:229], v[128:129], off offset:192
	global_load_dwordx4 v[230:233], v[112:113], off offset:192
	global_load_dwordx4 v[234:237], v[128:129], off offset:256
	global_load_dwordx4 v[238:241], v[112:113], off offset:256
	global_load_dwordx4 v[242:245], v[128:129], off offset:320
	global_load_dwordx4 v[246:249], v[112:113], off offset:320
	s_waitcnt vmcnt(11)
	v_pk_mul_f32 v[184:185], v[184:185], 0.5 op_sel_hi:[1,0]
	v_pk_mul_f32 v[186:187], v[186:187], 0.5 op_sel_hi:[1,0]
	s_waitcnt vmcnt(10)
	v_pk_fma_f32 v[120:121], v[158:159], v[184:185], v[198:199]
	v_pk_fma_f32 v[122:123], v[160:161], v[186:187], v[200:201]
	global_store_dwordx4 v[112:113], v[120:123], off
	s_nop 0
	s_waitcnt vmcnt(10)
	v_pk_mul_f32 v[210:211], v[210:211], 0.5 op_sel_hi:[1,0]
	v_pk_mul_f32 v[212:213], v[212:213], 0.5 op_sel_hi:[1,0]
	s_waitcnt vmcnt(9)
	v_pk_fma_f32 v[120:121], v[154:155], v[210:211], v[214:215]
	v_pk_fma_f32 v[122:123], v[156:157], v[212:213], v[216:217]
	global_store_dwordx4 v[112:113], v[120:123], off offset:64
	s_nop 0
	global_load_dwordx4 v[184:187], v[128:129], off offset:384
	global_load_dwordx4 v[198:201], v[112:113], off offset:384
	global_load_dwordx4 v[210:213], v[128:129], off offset:448
	global_load_dwordx4 v[214:217], v[112:113], off offset:448
	s_waitcnt vmcnt(13)
	v_pk_mul_f32 v[218:219], v[218:219], 0.5 op_sel_hi:[1,0]
	v_pk_mul_f32 v[220:221], v[220:221], 0.5 op_sel_hi:[1,0]
	s_waitcnt vmcnt(12)
	v_pk_fma_f32 v[120:121], v[150:151], v[218:219], v[222:223]
	v_pk_fma_f32 v[122:123], v[152:153], v[220:221], v[224:225]
	global_store_dwordx4 v[112:113], v[120:123], off offset:128
	s_nop 0
	s_waitcnt vmcnt(12)
	v_pk_mul_f32 v[226:227], v[226:227], 0.5 op_sel_hi:[1,0]
	v_pk_mul_f32 v[228:229], v[228:229], 0.5 op_sel_hi:[1,0]
	s_waitcnt vmcnt(11)
	v_pk_fma_f32 v[120:121], v[146:147], v[226:227], v[230:231]
	v_pk_fma_f32 v[122:123], v[148:149], v[228:229], v[232:233]
	global_store_dwordx4 v[112:113], v[120:123], off offset:192
	s_nop 0
	s_waitcnt vmcnt(11)
	v_pk_mul_f32 v[234:235], v[234:235], 0.5 op_sel_hi:[1,0]
	v_pk_mul_f32 v[236:237], v[236:237], 0.5 op_sel_hi:[1,0]
	s_waitcnt vmcnt(10)
	v_pk_fma_f32 v[120:121], v[134:135], v[234:235], v[238:239]
	v_pk_fma_f32 v[122:123], v[136:137], v[236:237], v[240:241]
	global_store_dwordx4 v[112:113], v[120:123], off offset:256
	s_nop 0
	s_waitcnt vmcnt(10)
	v_pk_mul_f32 v[242:243], v[242:243], 0.5 op_sel_hi:[1,0]
	v_pk_mul_f32 v[244:245], v[244:245], 0.5 op_sel_hi:[1,0]
	s_waitcnt vmcnt(9)
	v_pk_fma_f32 v[106:107], v[106:107], v[242:243], v[246:247]
	v_pk_fma_f32 v[108:109], v[108:109], v[244:245], v[248:249]
	global_store_dwordx4 v[112:113], v[106:109], off offset:320
	s_nop 0
	s_waitcnt vmcnt(7)
	v_pk_mul_f32 v[184:185], v[184:185], 0.5 op_sel_hi:[1,0]
	v_pk_mul_f32 v[186:187], v[186:187], 0.5 op_sel_hi:[1,0]
	s_waitcnt vmcnt(6)
	v_pk_fma_f32 v[102:103], v[102:103], v[184:185], v[198:199]
	v_pk_fma_f32 v[104:105], v[104:105], v[186:187], v[200:201]
	global_store_dwordx4 v[112:113], v[102:105], off offset:384
	s_nop 0
	s_waitcnt vmcnt(6)
	v_pk_mul_f32 v[210:211], v[210:211], 0.5 op_sel_hi:[1,0]
	v_pk_mul_f32 v[212:213], v[212:213], 0.5 op_sel_hi:[1,0]
	s_waitcnt vmcnt(5)
	v_pk_fma_f32 v[98:99], v[98:99], v[210:211], v[214:215]
	v_pk_fma_f32 v[100:101], v[100:101], v[212:213], v[216:217]
	global_store_dwordx4 v[112:113], v[98:101], off offset:448
	s_nop 0
	s_nop 1
	v_or_b32_e32 v98, 16, v114
	v_cmp_lt_i32_e32 vcc, s97, v98
	v_add_u32_e32 v100, 0xffffc010, v114
	v_ashrrev_i32_e32 v99, 31, v98
	v_cndmask_b32_e64 v99, v99, 0, vcc
	v_cndmask_b32_e32 v98, v98, v100, vcc
	v_cndmask_b32_e64 v102, v115, 8, vcc
	v_cndmask_b32_e32 v101, v116, v117, vcc
	v_cndmask_b32_e32 v100, v118, v119, vcc
	v_lshlrev_b64 v[98:99], 12, v[98:99]
	v_lshl_add_u64 v[98:99], v[100:101], 0, v[98:99]
	v_mul_hi_i32_i24_e32 v101, 0x9000, v102
	v_mul_i32_i24_e32 v100, 0x9000, v102
	v_lshl_add_u64 v[100:101], s[14:15], 0, v[100:101]
	v_lshl_add_u64 v[108:109], v[100:101], 0, v[110:111]
	global_load_dwordx4 v[184:187], v[108:109], off
	v_lshl_add_u64 v[98:99], v[98:99], 0, v[110:111]
	global_load_dwordx4 v[198:201], v[98:99], off
	global_load_dwordx4 v[210:213], v[108:109], off offset:64
	global_load_dwordx4 v[214:217], v[98:99], off offset:64
	global_load_dwordx4 v[218:221], v[108:109], off offset:128
	global_load_dwordx4 v[222:225], v[98:99], off offset:128
	global_load_dwordx4 v[226:229], v[108:109], off offset:192
	global_load_dwordx4 v[230:233], v[98:99], off offset:192
	global_load_dwordx4 v[234:237], v[108:109], off offset:256
	global_load_dwordx4 v[238:241], v[98:99], off offset:256
	global_load_dwordx4 v[242:245], v[108:109], off offset:320
	global_load_dwordx4 v[246:249], v[98:99], off offset:320
	s_waitcnt vmcnt(11)
	v_pk_mul_f32 v[184:185], v[184:185], 0.5 op_sel_hi:[1,0]
	v_pk_mul_f32 v[186:187], v[186:187], 0.5 op_sel_hi:[1,0]
	s_waitcnt vmcnt(10)
	v_pk_fma_f32 v[94:95], v[94:95], v[184:185], v[198:199]
	v_pk_fma_f32 v[96:97], v[96:97], v[186:187], v[200:201]
	global_store_dwordx4 v[98:99], v[94:97], off
	s_nop 0
	s_waitcnt vmcnt(10)
	v_pk_mul_f32 v[210:211], v[210:211], 0.5 op_sel_hi:[1,0]
	v_pk_mul_f32 v[212:213], v[212:213], 0.5 op_sel_hi:[1,0]
	s_waitcnt vmcnt(9)
	v_pk_fma_f32 v[90:91], v[90:91], v[210:211], v[214:215]
	v_pk_fma_f32 v[92:93], v[92:93], v[212:213], v[216:217]
	global_store_dwordx4 v[98:99], v[90:93], off offset:64
	s_nop 0
	global_load_dwordx4 v[184:187], v[108:109], off offset:384
	global_load_dwordx4 v[198:201], v[98:99], off offset:384
	global_load_dwordx4 v[210:213], v[108:109], off offset:448
	global_load_dwordx4 v[214:217], v[98:99], off offset:448
	s_waitcnt vmcnt(13)
	v_pk_mul_f32 v[218:219], v[218:219], 0.5 op_sel_hi:[1,0]
	v_pk_mul_f32 v[220:221], v[220:221], 0.5 op_sel_hi:[1,0]
	s_waitcnt vmcnt(12)
	v_pk_fma_f32 v[86:87], v[86:87], v[218:219], v[222:223]
	v_pk_fma_f32 v[88:89], v[88:89], v[220:221], v[224:225]
	global_store_dwordx4 v[98:99], v[86:89], off offset:128
	s_nop 0
	s_waitcnt vmcnt(12)
	v_pk_mul_f32 v[226:227], v[226:227], 0.5 op_sel_hi:[1,0]
	v_pk_mul_f32 v[228:229], v[228:229], 0.5 op_sel_hi:[1,0]
	s_waitcnt vmcnt(11)
	v_pk_fma_f32 v[82:83], v[82:83], v[226:227], v[230:231]
	v_pk_fma_f32 v[84:85], v[84:85], v[228:229], v[232:233]
	global_store_dwordx4 v[98:99], v[82:85], off offset:192
	s_nop 0
	s_waitcnt vmcnt(11)
	v_pk_mul_f32 v[234:235], v[234:235], 0.5 op_sel_hi:[1,0]
	v_pk_mul_f32 v[236:237], v[236:237], 0.5 op_sel_hi:[1,0]
	s_waitcnt vmcnt(10)
	v_pk_fma_f32 v[78:79], v[78:79], v[234:235], v[238:239]
	v_pk_fma_f32 v[80:81], v[80:81], v[236:237], v[240:241]
	global_store_dwordx4 v[98:99], v[78:81], off offset:256
	s_nop 0
	s_waitcnt vmcnt(10)
	v_pk_mul_f32 v[242:243], v[242:243], 0.5 op_sel_hi:[1,0]
	v_pk_mul_f32 v[244:245], v[244:245], 0.5 op_sel_hi:[1,0]
	s_waitcnt vmcnt(9)
	v_pk_fma_f32 v[74:75], v[74:75], v[242:243], v[246:247]
	v_pk_fma_f32 v[76:77], v[76:77], v[244:245], v[248:249]
	global_store_dwordx4 v[98:99], v[74:77], off offset:320
	s_nop 0
	s_waitcnt vmcnt(7)
	v_pk_mul_f32 v[184:185], v[184:185], 0.5 op_sel_hi:[1,0]
	v_pk_mul_f32 v[186:187], v[186:187], 0.5 op_sel_hi:[1,0]
	s_waitcnt vmcnt(6)
	v_pk_fma_f32 v[70:71], v[70:71], v[184:185], v[198:199]
	v_pk_fma_f32 v[72:73], v[72:73], v[186:187], v[200:201]
	global_store_dwordx4 v[98:99], v[70:73], off offset:384
	s_nop 0
	s_waitcnt vmcnt(6)
	v_pk_mul_f32 v[210:211], v[210:211], 0.5 op_sel_hi:[1,0]
	v_pk_mul_f32 v[212:213], v[212:213], 0.5 op_sel_hi:[1,0]
	s_waitcnt vmcnt(5)
	v_pk_fma_f32 v[66:67], v[66:67], v[210:211], v[214:215]
	v_pk_fma_f32 v[68:69], v[68:69], v[212:213], v[216:217]
	global_store_dwordx4 v[98:99], v[66:69], off offset:448
	s_nop 0
	s_nop 1
	v_or_b32_e32 v66, 32, v114
	v_cmp_lt_i32_e32 vcc, s97, v66
	v_add_u32_e32 v68, 0xffffc020, v114
	v_ashrrev_i32_e32 v67, 31, v66
	v_cndmask_b32_e64 v67, v67, 0, vcc
	v_cndmask_b32_e32 v66, v66, v68, vcc
	v_cndmask_b32_e64 v70, v115, 8, vcc
	v_cndmask_b32_e32 v69, v116, v117, vcc
	v_cndmask_b32_e32 v68, v118, v119, vcc
	v_lshlrev_b64 v[66:67], 12, v[66:67]
	v_lshl_add_u64 v[66:67], v[68:69], 0, v[66:67]
	v_mul_hi_i32_i24_e32 v69, 0x9000, v70
	v_mul_i32_i24_e32 v68, 0x9000, v70
	v_lshl_add_u64 v[68:69], s[14:15], 0, v[68:69]
	v_lshl_add_u64 v[76:77], v[68:69], 0, v[110:111]
	global_load_dwordx4 v[184:187], v[76:77], off
	v_lshl_add_u64 v[66:67], v[66:67], 0, v[110:111]
	global_load_dwordx4 v[198:201], v[66:67], off
	global_load_dwordx4 v[210:213], v[76:77], off offset:64
	global_load_dwordx4 v[214:217], v[66:67], off offset:64
	global_load_dwordx4 v[218:221], v[76:77], off offset:128
	global_load_dwordx4 v[222:225], v[66:67], off offset:128
	global_load_dwordx4 v[226:229], v[76:77], off offset:192
	global_load_dwordx4 v[230:233], v[66:67], off offset:192
	global_load_dwordx4 v[234:237], v[76:77], off offset:256
	global_load_dwordx4 v[238:241], v[66:67], off offset:256
	global_load_dwordx4 v[242:245], v[76:77], off offset:320
	global_load_dwordx4 v[246:249], v[66:67], off offset:320
	s_waitcnt vmcnt(11)
	v_pk_mul_f32 v[184:185], v[184:185], 0.5 op_sel_hi:[1,0]
	v_pk_mul_f32 v[186:187], v[186:187], 0.5 op_sel_hi:[1,0]
	s_waitcnt vmcnt(10)
	v_pk_fma_f32 v[62:63], v[62:63], v[184:185], v[198:199]
	v_pk_fma_f32 v[64:65], v[64:65], v[186:187], v[200:201]
	global_store_dwordx4 v[66:67], v[62:65], off
	s_nop 0
	s_waitcnt vmcnt(10)
	v_pk_mul_f32 v[210:211], v[210:211], 0.5 op_sel_hi:[1,0]
	v_pk_mul_f32 v[212:213], v[212:213], 0.5 op_sel_hi:[1,0]
	s_waitcnt vmcnt(9)
	v_pk_fma_f32 v[58:59], v[58:59], v[210:211], v[214:215]
	v_pk_fma_f32 v[60:61], v[60:61], v[212:213], v[216:217]
	global_store_dwordx4 v[66:67], v[58:61], off offset:64
	s_nop 0
	global_load_dwordx4 v[184:187], v[76:77], off offset:384
	global_load_dwordx4 v[198:201], v[66:67], off offset:384
	global_load_dwordx4 v[210:213], v[76:77], off offset:448
	global_load_dwordx4 v[214:217], v[66:67], off offset:448
	s_waitcnt vmcnt(13)
	v_pk_mul_f32 v[218:219], v[218:219], 0.5 op_sel_hi:[1,0]
	v_pk_mul_f32 v[220:221], v[220:221], 0.5 op_sel_hi:[1,0]
	s_waitcnt vmcnt(12)
	v_pk_fma_f32 v[54:55], v[54:55], v[218:219], v[222:223]
	v_pk_fma_f32 v[56:57], v[56:57], v[220:221], v[224:225]
	global_store_dwordx4 v[66:67], v[54:57], off offset:128
	s_nop 0
	s_waitcnt vmcnt(12)
	v_pk_mul_f32 v[226:227], v[226:227], 0.5 op_sel_hi:[1,0]
	v_pk_mul_f32 v[228:229], v[228:229], 0.5 op_sel_hi:[1,0]
	s_waitcnt vmcnt(11)
	v_pk_fma_f32 v[50:51], v[50:51], v[226:227], v[230:231]
	v_pk_fma_f32 v[52:53], v[52:53], v[228:229], v[232:233]
	global_store_dwordx4 v[66:67], v[50:53], off offset:192
	s_nop 0
	s_waitcnt vmcnt(11)
	v_pk_mul_f32 v[234:235], v[234:235], 0.5 op_sel_hi:[1,0]
	v_pk_mul_f32 v[236:237], v[236:237], 0.5 op_sel_hi:[1,0]
	s_waitcnt vmcnt(10)
	v_pk_fma_f32 v[46:47], v[46:47], v[234:235], v[238:239]
	v_pk_fma_f32 v[48:49], v[48:49], v[236:237], v[240:241]
	global_store_dwordx4 v[66:67], v[46:49], off offset:256
	s_nop 0
	s_waitcnt vmcnt(10)
	v_pk_mul_f32 v[242:243], v[242:243], 0.5 op_sel_hi:[1,0]
	v_pk_mul_f32 v[244:245], v[244:245], 0.5 op_sel_hi:[1,0]
	s_waitcnt vmcnt(9)
	v_pk_fma_f32 v[42:43], v[42:43], v[242:243], v[246:247]
	v_pk_fma_f32 v[44:45], v[44:45], v[244:245], v[248:249]
	global_store_dwordx4 v[66:67], v[42:45], off offset:320
	s_nop 0
	s_waitcnt vmcnt(7)
	v_pk_mul_f32 v[184:185], v[184:185], 0.5 op_sel_hi:[1,0]
	v_pk_mul_f32 v[186:187], v[186:187], 0.5 op_sel_hi:[1,0]
	s_waitcnt vmcnt(6)
	v_pk_fma_f32 v[38:39], v[38:39], v[184:185], v[198:199]
	v_pk_fma_f32 v[40:41], v[40:41], v[186:187], v[200:201]
	global_store_dwordx4 v[66:67], v[38:41], off offset:384
	s_nop 0
	s_waitcnt vmcnt(6)
	v_pk_mul_f32 v[210:211], v[210:211], 0.5 op_sel_hi:[1,0]
	v_pk_mul_f32 v[212:213], v[212:213], 0.5 op_sel_hi:[1,0]
	s_waitcnt vmcnt(5)
	v_pk_fma_f32 v[34:35], v[34:35], v[210:211], v[214:215]
	v_pk_fma_f32 v[36:37], v[36:37], v[212:213], v[216:217]
	global_store_dwordx4 v[66:67], v[34:37], off offset:448
	s_nop 0
	s_nop 1
	v_or_b32_e32 v34, 48, v114
	v_cmp_lt_i32_e32 vcc, s97, v34
	v_add_u32_e32 v36, 0xffffc030, v114
	v_ashrrev_i32_e32 v35, 31, v34
	v_cndmask_b32_e64 v35, v35, 0, vcc
	v_cndmask_b32_e32 v34, v34, v36, vcc
	v_cndmask_b32_e64 v38, v115, 8, vcc
	v_cndmask_b32_e32 v37, v116, v117, vcc
	v_cndmask_b32_e32 v36, v118, v119, vcc
	v_lshlrev_b64 v[34:35], 12, v[34:35]
	v_lshl_add_u64 v[34:35], v[36:37], 0, v[34:35]
	v_mul_hi_i32_i24_e32 v37, 0x9000, v38
	v_mul_i32_i24_e32 v36, 0x9000, v38
	v_lshl_add_u64 v[36:37], s[14:15], 0, v[36:37]
	v_lshl_add_u64 v[44:45], v[36:37], 0, v[110:111]
	global_load_dwordx4 v[184:187], v[44:45], off
	v_lshl_add_u64 v[34:35], v[34:35], 0, v[110:111]
	global_load_dwordx4 v[198:201], v[34:35], off
	global_load_dwordx4 v[210:213], v[44:45], off offset:64
	global_load_dwordx4 v[214:217], v[34:35], off offset:64
	global_load_dwordx4 v[218:221], v[44:45], off offset:128
	global_load_dwordx4 v[222:225], v[34:35], off offset:128
	global_load_dwordx4 v[226:229], v[44:45], off offset:192
	global_load_dwordx4 v[230:233], v[34:35], off offset:192
	global_load_dwordx4 v[234:237], v[44:45], off offset:256
	global_load_dwordx4 v[238:241], v[34:35], off offset:256
	global_load_dwordx4 v[242:245], v[44:45], off offset:320
	global_load_dwordx4 v[246:249], v[34:35], off offset:320
	s_waitcnt vmcnt(11)
	v_pk_mul_f32 v[184:185], v[184:185], 0.5 op_sel_hi:[1,0]
	v_pk_mul_f32 v[186:187], v[186:187], 0.5 op_sel_hi:[1,0]
	s_waitcnt vmcnt(10)
	v_pk_fma_f32 v[30:31], v[30:31], v[184:185], v[198:199]
	v_pk_fma_f32 v[32:33], v[32:33], v[186:187], v[200:201]
	global_store_dwordx4 v[34:35], v[30:33], off
	s_nop 0
	s_waitcnt vmcnt(10)
	v_pk_mul_f32 v[210:211], v[210:211], 0.5 op_sel_hi:[1,0]
	v_pk_mul_f32 v[212:213], v[212:213], 0.5 op_sel_hi:[1,0]
	s_waitcnt vmcnt(9)
	v_pk_fma_f32 v[26:27], v[26:27], v[210:211], v[214:215]
	v_pk_fma_f32 v[28:29], v[28:29], v[212:213], v[216:217]
	global_store_dwordx4 v[34:35], v[26:29], off offset:64
	s_nop 0
	global_load_dwordx4 v[184:187], v[44:45], off offset:384
	global_load_dwordx4 v[198:201], v[34:35], off offset:384
	global_load_dwordx4 v[210:213], v[44:45], off offset:448
	global_load_dwordx4 v[214:217], v[34:35], off offset:448
	s_waitcnt vmcnt(13)
	v_pk_mul_f32 v[218:219], v[218:219], 0.5 op_sel_hi:[1,0]
	v_pk_mul_f32 v[220:221], v[220:221], 0.5 op_sel_hi:[1,0]
	s_waitcnt vmcnt(12)
	v_pk_fma_f32 v[22:23], v[22:23], v[218:219], v[222:223]
	v_pk_fma_f32 v[24:25], v[24:25], v[220:221], v[224:225]
	global_store_dwordx4 v[34:35], v[22:25], off offset:128
	s_nop 0
	s_waitcnt vmcnt(12)
	v_pk_mul_f32 v[226:227], v[226:227], 0.5 op_sel_hi:[1,0]
	v_pk_mul_f32 v[228:229], v[228:229], 0.5 op_sel_hi:[1,0]
	s_waitcnt vmcnt(11)
	v_pk_fma_f32 v[18:19], v[18:19], v[226:227], v[230:231]
	v_pk_fma_f32 v[20:21], v[20:21], v[228:229], v[232:233]
	global_store_dwordx4 v[34:35], v[18:21], off offset:192
	s_nop 0
	s_waitcnt vmcnt(11)
	v_pk_mul_f32 v[234:235], v[234:235], 0.5 op_sel_hi:[1,0]
	v_pk_mul_f32 v[236:237], v[236:237], 0.5 op_sel_hi:[1,0]
	s_waitcnt vmcnt(10)
	v_pk_fma_f32 v[14:15], v[14:15], v[234:235], v[238:239]
	v_pk_fma_f32 v[16:17], v[16:17], v[236:237], v[240:241]
	global_store_dwordx4 v[34:35], v[14:17], off offset:256
	s_nop 0
	s_waitcnt vmcnt(10)
	v_pk_mul_f32 v[242:243], v[242:243], 0.5 op_sel_hi:[1,0]
	v_pk_mul_f32 v[244:245], v[244:245], 0.5 op_sel_hi:[1,0]
	s_waitcnt vmcnt(9)
	v_pk_fma_f32 v[10:11], v[10:11], v[242:243], v[246:247]
	v_pk_fma_f32 v[12:13], v[12:13], v[244:245], v[248:249]
	global_store_dwordx4 v[34:35], v[10:13], off offset:320
	s_nop 0
	s_waitcnt vmcnt(7)
	v_pk_mul_f32 v[184:185], v[184:185], 0.5 op_sel_hi:[1,0]
	v_pk_mul_f32 v[186:187], v[186:187], 0.5 op_sel_hi:[1,0]
	s_waitcnt vmcnt(6)
	v_pk_fma_f32 v[6:7], v[6:7], v[184:185], v[198:199]
	v_pk_fma_f32 v[8:9], v[8:9], v[186:187], v[200:201]
	global_store_dwordx4 v[34:35], v[6:9], off offset:384
	s_nop 0
	s_waitcnt vmcnt(6)
	v_pk_mul_f32 v[210:211], v[210:211], 0.5 op_sel_hi:[1,0]
	v_pk_mul_f32 v[212:213], v[212:213], 0.5 op_sel_hi:[1,0]
	s_waitcnt vmcnt(5)
	v_pk_fma_f32 v[2:3], v[2:3], v[210:211], v[214:215]
	v_pk_fma_f32 v[4:5], v[4:5], v[212:213], v[216:217]
	global_store_dwordx4 v[34:35], v[2:5], off offset:448
	s_nop 0
	s_add_i32 s18, s18, s11
	s_cmpk_gt_i32 s18, 0xff
	s_cbranch_scc0 .LBB0_1527
